# G3 residual epilogue operands staged by full-line LDS-DMA; both wave halves enter EpiRes epilogues together
# speedup vs baseline: 1.0468x; 1.0054x over previous
; #define PG8_STAGE(bufoff, gbase, voff) do { _Pragma("unroll") for (int _i = 0; _i < 2; ++_i) \
;         __builtin_amdgcn_global_load_lds((const unsigned*)((const char*)(gbase) + (voff)[_i]), (PG8_LAS unsigned*)(lds + (bufoff) + ldsw + _i * 8192), 16, 0, 0); } while (0)
; #define PG8_LDA(dst, b, h) do { _Pragma("unroll") for (int m = 0; m < 4; ++m) _Pragma("unroll") for (int k = 0; k < 2; ++k) dst[m][k] = *(const PG8_LAS bf16x8*)(lds + PG8_SA(b, h) + aoff + m * 2048 + k * 1024); } while (0)
; #define PG8_LDB(dst, b, h) do { _Pragma("unroll") for (int n = 0; n < 2; ++n) _Pragma("unroll") for (int k = 0; k < 2; ++k) dst[n][k] = *(const PG8_LAS bf16x8*)(lds + PG8_SB(b, h) + boff + n * 2048 + k * 1024); } while (0)
; #define PG8_MMA(ai, bj, At, Bt) do { __builtin_amdgcn_s_setprio(1); _Pragma("unroll") for (int m = 0; m < 4; ++m) _Pragma("unroll") for (int n = 0; n < 2; ++n) _Pragma("unroll") for (int k = 0; k < 2; ++k) \
;         acc[ai][bj][m][n] = __builtin_amdgcn_mfma_f32_16x16x32_bf16(Bt[n][k], At[m][k], acc[ai][bj][m][n], 0, 0, 0); __builtin_amdgcn_s_setprio(0); } while (0)
; #define PG8_WAIT_V(n) asm volatile("s_waitcnt vmcnt(" #n ")" ::: "memory")
; #define PG8_WAIT_L(n) asm volatile("s_waitcnt lgkmcnt(" #n ")" ::: "memory")
; #define PG8_BAR __builtin_amdgcn_s_barrier()
; #define PG8_SCHED __builtin_amdgcn_sched_barrier(0)
; template <class Epi, class Sched, bool ALIGN_EPI = false, bool SP2 = false>
; __device__ __forceinline__ void gemm_phase(PG8_LAS unsigned char* lds, const Gemm g, const Sched& S, const Epi& E, const int tid) {
;     ...
;             PG8_LDB(B0, 0, 0); PG8_LDB(B1, 0, 1); PG8_SCHED; PG8_LDA(At, 0, 0); PG8_STAGE(PG8_SA(1, 1), a1 + hstep, voffA);
;             PG8_WAIT_V(8); PG8_WAIT_L(0); PG8_BAR; PG8_MMA(0, 0, At, B0); PG8_MMA(0, 1, At, B1); PG8_BAR; PG8_SCHED;
;             PG8_LDA(At, 0, 1); PG8_STAGE(PG8_SB(0, 0), b2, voffB); PG8_STAGE(PG8_SB(0, 1), b2 + hstep, voffB); PG8_STAGE(PG8_SA(0, 0), a2, voffA);
;             PG8_WAIT_V(8); PG8_WAIT_L(0); PG8_BAR; PG8_MMA(1, 0, At, B0); PG8_MMA(1, 1, At, B1); PG8_BAR; PG8_SCHED;
.LBB0_44:
	s_add_u32 s0, s8, 0xfff80080
	s_addc_u32 s1, s9, -1
	s_add_i32 s30, 0, 0x10000
	s_cmp_eq_u32 s29, 28
	s_cselect_b32 s3, s10, s1
	s_cselect_b32 s2, s11, s0
	s_cselect_b32 s1, s23, s28
	s_cselect_b32 s0, s26, s27
	s_add_i32 s34, 0, 0x14000
	v_add_u32_e32 v148, s30, v236
	v_add_u32_e32 v164, s34, v236
	ds_read_b128 v[136:139], v148
	ds_read_b128 v[140:143], v148 offset:1024
	ds_read_b128 v[144:147], v148 offset:2048
	ds_read_b128 v[148:151], v148 offset:3072
	ds_read_b128 v[152:155], v164
	ds_read_b128 v[156:159], v164 offset:1024
	ds_read_b128 v[160:163], v164 offset:2048
	ds_read_b128 v[164:167], v164 offset:3072
	v_lshl_add_u64 v[180:181], s[8:9], 0, v[132:133]
	s_add_i32 m0, s5, 0xc000
	ds_read_b128 v[168:171], v238
	ds_read_b128 v[172:175], v238 offset:1024
	ds_read_b128 v[176:179], v238 offset:2048
	ds_read_b128 v[192:195], v238 offset:3072
	ds_read_b128 v[196:199], v238 offset:4096
	ds_read_b128 v[200:203], v238 offset:5120
	ds_read_b128 v[204:207], v238 offset:6144
	ds_read_b128 v[208:211], v238 offset:7168
	global_load_lds_dwordx4 v[180:181], off
	v_lshl_add_u64 v[180:181], s[8:9], 0, v[134:135]
	s_add_i32 m0, s5, 0xe000
	s_nop 0
	global_load_lds_dwordx4 v[180:181], off
	s_waitcnt vmcnt(8)
	s_waitcnt lgkmcnt(0)
	s_barrier
	s_setprio 1
	s_waitcnt lgkmcnt(0)
	v_mfma_f32_16x16x32_bf16 v[126:129], v[136:139], v[168:171], v[126:129]
	v_mfma_f32_16x16x32_bf16 v[122:125], v[144:147], v[168:171], v[122:125]
	v_mfma_f32_16x16x32_bf16 v[110:113], v[136:139], v[176:179], v[110:113]
	v_mfma_f32_16x16x32_bf16 v[106:109], v[144:147], v[176:179], v[106:109]
	v_mfma_f32_16x16x32_bf16 v[94:97], v[136:139], v[196:199], v[94:97]
	v_mfma_f32_16x16x32_bf16 v[90:93], v[144:147], v[196:199], v[90:93]
	v_mfma_f32_16x16x32_bf16 v[78:81], v[136:139], v[204:207], v[78:81]
	v_mfma_f32_16x16x32_bf16 v[74:77], v[144:147], v[204:207], v[74:77]
	v_mfma_f32_16x16x32_bf16 v[126:129], v[140:143], v[172:175], v[126:129]
	v_mfma_f32_16x16x32_bf16 v[122:125], v[148:151], v[172:175], v[122:125]
	v_mfma_f32_16x16x32_bf16 v[110:113], v[140:143], v[192:195], v[110:113]
	v_mfma_f32_16x16x32_bf16 v[106:109], v[148:151], v[192:195], v[106:109]
	v_mfma_f32_16x16x32_bf16 v[94:97], v[140:143], v[200:203], v[94:97]
	v_mfma_f32_16x16x32_bf16 v[90:93], v[148:151], v[200:203], v[90:93]
	v_mfma_f32_16x16x32_bf16 v[78:81], v[140:143], v[208:211], v[78:81]
	v_mfma_f32_16x16x32_bf16 v[74:77], v[148:151], v[208:211], v[74:77]
	s_setprio 0
	s_setprio 1
	v_mfma_f32_16x16x32_bf16 v[118:121], v[152:155], v[168:171], v[118:121]
	v_mfma_f32_16x16x32_bf16 v[114:117], v[160:163], v[168:171], v[114:117]
	v_mfma_f32_16x16x32_bf16 v[102:105], v[152:155], v[176:179], v[102:105]
	v_mfma_f32_16x16x32_bf16 v[98:101], v[160:163], v[176:179], v[98:101]
	v_mfma_f32_16x16x32_bf16 v[86:89], v[152:155], v[196:199], v[86:89]
	v_mfma_f32_16x16x32_bf16 v[82:85], v[160:163], v[196:199], v[82:85]
	v_mfma_f32_16x16x32_bf16 v[70:73], v[152:155], v[204:207], v[70:73]
	v_mfma_f32_16x16x32_bf16 v[66:69], v[160:163], v[204:207], v[66:69]
	v_mfma_f32_16x16x32_bf16 v[118:121], v[156:159], v[172:175], v[118:121]
	v_mfma_f32_16x16x32_bf16 v[114:117], v[164:167], v[172:175], v[114:117]
	v_mfma_f32_16x16x32_bf16 v[102:105], v[156:159], v[192:195], v[102:105]
	v_mfma_f32_16x16x32_bf16 v[98:101], v[164:167], v[192:195], v[98:101]
	v_mfma_f32_16x16x32_bf16 v[86:89], v[156:159], v[200:203], v[86:89]
	v_mfma_f32_16x16x32_bf16 v[82:85], v[164:167], v[200:203], v[82:85]
	v_mfma_f32_16x16x32_bf16 v[70:73], v[156:159], v[208:211], v[70:73]
	v_mfma_f32_16x16x32_bf16 v[66:69], v[164:167], v[208:211], v[66:69]
	s_setprio 0
	s_barrier
	s_add_i32 s30, s30, s16
	v_lshl_add_u64 v[180:181], s[0:1], 0, v[0:1]
	s_mov_b32 m0, s30
	ds_read_b128 v[168:171], v238 offset:16384
	ds_read_b128 v[172:175], v238 offset:17408
	ds_read_b128 v[176:179], v238 offset:18432
	ds_read_b128 v[192:195], v238 offset:19456
	ds_read_b128 v[196:199], v238 offset:20480
	ds_read_b128 v[200:203], v238 offset:21504
	ds_read_b128 v[204:207], v238 offset:22528
	ds_read_b128 v[208:211], v238 offset:23552
	global_load_lds_dwordx4 v[180:181], off
	s_add_i32 m0, s30, 0x2000
	s_add_u32 s30, s0, 0x80000
	v_lshl_add_u64 v[212:213], s[0:1], 0, v[130:131]
	s_addc_u32 s31, s1, 0
	s_add_i32 s34, s34, s16
	global_load_lds_dwordx4 v[212:213], off
	v_lshl_add_u64 v[222:223], s[30:31], 0, v[0:1]
	s_mov_b32 m0, s34
	v_lshl_add_u64 v[226:227], s[2:3], 0, v[130:131]
	global_load_lds_dwordx4 v[222:223], off
	v_lshl_add_u64 v[222:223], s[30:31], 0, v[130:131]
	s_add_i32 m0, s34, 0x2000
	s_nop 0
	global_load_lds_dwordx4 v[222:223], off
	v_lshl_add_u64 v[222:223], s[2:3], 0, v[0:1]
	s_mov_b32 m0, s5
	s_nop 0
	global_load_lds_dwordx4 v[222:223], off
	s_mov_b32 m0, s7
	s_nop 0
	global_load_lds_dwordx4 v[226:227], off
	s_waitcnt vmcnt(8)
	s_waitcnt lgkmcnt(0)
	s_barrier
; #define PG8_STAGE(bufoff, gbase, voff) do { _Pragma("unroll") for (int _i = 0; _i < 2; ++_i) \
;         __builtin_amdgcn_global_load_lds((const unsigned*)((const char*)(gbase) + (voff)[_i]), (PG8_LAS unsigned*)(lds + (bufoff) + ldsw + _i * 8192), 16, 0, 0); } while (0)
; #define PG8_LDA(dst, b, h) do { _Pragma("unroll") for (int m = 0; m < 4; ++m) _Pragma("unroll") for (int k = 0; k < 2; ++k) dst[m][k] = *(const PG8_LAS bf16x8*)(lds + PG8_SA(b, h) + aoff + m * 2048 + k * 1024); } while (0)
; #define PG8_LDB(dst, b, h) do { _Pragma("unroll") for (int n = 0; n < 2; ++n) _Pragma("unroll") for (int k = 0; k < 2; ++k) dst[n][k] = *(const PG8_LAS bf16x8*)(lds + PG8_SB(b, h) + boff + n * 2048 + k * 1024); } while (0)
; #define PG8_MMA(ai, bj, At, Bt) do { __builtin_amdgcn_s_setprio(1); _Pragma("unroll") for (int m = 0; m < 4; ++m) _Pragma("unroll") for (int n = 0; n < 2; ++n) _Pragma("unroll") for (int k = 0; k < 2; ++k) \
;         acc[ai][bj][m][n] = __builtin_amdgcn_mfma_f32_16x16x32_bf16(Bt[n][k], At[m][k], acc[ai][bj][m][n], 0, 0, 0); __builtin_amdgcn_s_setprio(0); } while (0)
; #define PG8_WAIT_V(n) asm volatile("s_waitcnt vmcnt(" #n ")" ::: "memory")
; #define PG8_WAIT_L(n) asm volatile("s_waitcnt lgkmcnt(" #n ")" ::: "memory")
; #define PG8_BAR __builtin_amdgcn_s_barrier()
; #define PG8_SCHED __builtin_amdgcn_sched_barrier(0)
; template <class Epi, class Sched, bool ALIGN_EPI = false, bool SP2 = false>
; __device__ __forceinline__ void gemm_phase(PG8_LAS unsigned char* lds, const Gemm g, const Sched& S, const Epi& E, const int tid) {
;     ...
;             PG8_WAIT_V(8); PG8_WAIT_L(0); PG8_BAR; PG8_MMA(1, 0, At, B0); PG8_MMA(1, 1, At, B1); PG8_BAR; PG8_SCHED;
;             PG8_LDB(B0, 1, 0); PG8_LDB(B1, 1, 1); PG8_SCHED; PG8_LDA(At, 1, 0); PG8_STAGE(PG8_SA(0, 1), a2 + hstep, voffA);
;             PG8_WAIT_V(8); PG8_WAIT_L(0); PG8_BAR; PG8_MMA(0, 0, At, B0); PG8_MMA(0, 1, At, B1); PG8_BAR; PG8_SCHED;
	s_setprio 1
	s_waitcnt lgkmcnt(0)
	v_mfma_f32_16x16x32_bf16 v[62:65], v[136:139], v[168:171], v[62:65]
	v_mfma_f32_16x16x32_bf16 v[58:61], v[144:147], v[168:171], v[58:61]
	v_mfma_f32_16x16x32_bf16 v[46:49], v[136:139], v[176:179], v[46:49]
	v_mfma_f32_16x16x32_bf16 v[42:45], v[144:147], v[176:179], v[42:45]
	v_mfma_f32_16x16x32_bf16 v[30:33], v[136:139], v[196:199], v[30:33]
	v_mfma_f32_16x16x32_bf16 v[26:29], v[144:147], v[196:199], v[26:29]
	v_mfma_f32_16x16x32_bf16 v[14:17], v[136:139], v[204:207], v[14:17]
	v_mfma_f32_16x16x32_bf16 v[10:13], v[144:147], v[204:207], v[10:13]
	v_mfma_f32_16x16x32_bf16 v[62:65], v[140:143], v[172:175], v[62:65]
	v_mfma_f32_16x16x32_bf16 v[58:61], v[148:151], v[172:175], v[58:61]
	v_mfma_f32_16x16x32_bf16 v[46:49], v[140:143], v[192:195], v[46:49]
	v_mfma_f32_16x16x32_bf16 v[42:45], v[148:151], v[192:195], v[42:45]
	v_mfma_f32_16x16x32_bf16 v[30:33], v[140:143], v[200:203], v[30:33]
	v_mfma_f32_16x16x32_bf16 v[26:29], v[148:151], v[200:203], v[26:29]
	v_mfma_f32_16x16x32_bf16 v[14:17], v[140:143], v[208:211], v[14:17]
	v_mfma_f32_16x16x32_bf16 v[10:13], v[148:151], v[208:211], v[10:13]
	s_setprio 0
	s_setprio 1
	v_mfma_f32_16x16x32_bf16 v[54:57], v[152:155], v[168:171], v[54:57]
	v_mfma_f32_16x16x32_bf16 v[50:53], v[160:163], v[168:171], v[50:53]
	v_mfma_f32_16x16x32_bf16 v[38:41], v[152:155], v[176:179], v[38:41]
	v_mfma_f32_16x16x32_bf16 v[34:37], v[160:163], v[176:179], v[34:37]
	v_mfma_f32_16x16x32_bf16 v[22:25], v[152:155], v[196:199], v[22:25]
	v_mfma_f32_16x16x32_bf16 v[18:21], v[160:163], v[196:199], v[18:21]
	v_mfma_f32_16x16x32_bf16 v[6:9], v[152:155], v[204:207], v[6:9]
	v_mfma_f32_16x16x32_bf16 v[2:5], v[160:163], v[204:207], v[2:5]
	v_mfma_f32_16x16x32_bf16 v[54:57], v[156:159], v[172:175], v[54:57]
	v_mfma_f32_16x16x32_bf16 v[50:53], v[164:167], v[172:175], v[50:53]
	v_mfma_f32_16x16x32_bf16 v[38:41], v[156:159], v[192:195], v[38:41]
	v_mfma_f32_16x16x32_bf16 v[34:37], v[164:167], v[192:195], v[34:37]
	v_mfma_f32_16x16x32_bf16 v[22:25], v[156:159], v[200:203], v[22:25]
	v_mfma_f32_16x16x32_bf16 v[18:21], v[164:167], v[200:203], v[18:21]
	v_mfma_f32_16x16x32_bf16 v[6:9], v[156:159], v[208:211], v[6:9]
	v_mfma_f32_16x16x32_bf16 v[2:5], v[164:167], v[208:211], v[2:5]
	s_setprio 0
	s_barrier
	s_add_i32 s30, 0, 0x18000
	s_add_i32 s31, 0, 0x1c000
	v_add_u32_e32 v148, s30, v236
	v_add_u32_e32 v164, s31, v236
	ds_read_b128 v[136:139], v148
	ds_read_b128 v[140:143], v148 offset:1024
	ds_read_b128 v[144:147], v148 offset:2048
	ds_read_b128 v[148:151], v148 offset:3072
	ds_read_b128 v[152:155], v164
	ds_read_b128 v[156:159], v164 offset:1024
	ds_read_b128 v[160:163], v164 offset:2048
	ds_read_b128 v[164:167], v164 offset:3072
	s_add_u32 s2, s2, 0x80000
	s_addc_u32 s3, s3, 0
	s_mov_b32 m0, s17
	v_lshl_add_u64 v[240:241], s[2:3], 0, v[0:1]
	ds_read_b128 v[168:171], v238 offset:32768
	ds_read_b128 v[172:175], v238 offset:33792
	ds_read_b128 v[176:179], v238 offset:34816
	ds_read_b128 v[192:195], v238 offset:35840
	ds_read_b128 v[196:199], v238 offset:36864
	ds_read_b128 v[200:203], v238 offset:37888
	ds_read_b128 v[204:207], v238 offset:38912
	ds_read_b128 v[208:211], v238 offset:39936
	global_load_lds_dwordx4 v[240:241], off
	v_lshl_add_u64 v[240:241], s[2:3], 0, v[130:131]
	s_mov_b32 m0, s18
	s_nop 0
	global_load_lds_dwordx4 v[240:241], off
	s_waitcnt vmcnt(8)
	s_waitcnt lgkmcnt(0)
	s_barrier
	s_setprio 1
	s_waitcnt lgkmcnt(0)
	v_mfma_f32_16x16x32_bf16 v[126:129], v[136:139], v[168:171], v[126:129]
	v_mfma_f32_16x16x32_bf16 v[122:125], v[144:147], v[168:171], v[122:125]
	v_mfma_f32_16x16x32_bf16 v[110:113], v[136:139], v[176:179], v[110:113]
	v_mfma_f32_16x16x32_bf16 v[106:109], v[144:147], v[176:179], v[106:109]
	v_mfma_f32_16x16x32_bf16 v[94:97], v[136:139], v[196:199], v[94:97]
	v_mfma_f32_16x16x32_bf16 v[90:93], v[144:147], v[196:199], v[90:93]
	v_mfma_f32_16x16x32_bf16 v[78:81], v[136:139], v[204:207], v[78:81]
	v_mfma_f32_16x16x32_bf16 v[74:77], v[144:147], v[204:207], v[74:77]
	v_mfma_f32_16x16x32_bf16 v[126:129], v[140:143], v[172:175], v[126:129]
	v_mfma_f32_16x16x32_bf16 v[122:125], v[148:151], v[172:175], v[122:125]
	v_mfma_f32_16x16x32_bf16 v[110:113], v[140:143], v[192:195], v[110:113]
	v_mfma_f32_16x16x32_bf16 v[106:109], v[148:151], v[192:195], v[106:109]
	v_mfma_f32_16x16x32_bf16 v[94:97], v[140:143], v[200:203], v[94:97]
	v_mfma_f32_16x16x32_bf16 v[90:93], v[148:151], v[200:203], v[90:93]
	v_mfma_f32_16x16x32_bf16 v[78:81], v[140:143], v[208:211], v[78:81]
	v_mfma_f32_16x16x32_bf16 v[74:77], v[148:151], v[208:211], v[74:77]
	s_setprio 0
	s_setprio 1
	v_mfma_f32_16x16x32_bf16 v[118:121], v[152:155], v[168:171], v[118:121]
	v_mfma_f32_16x16x32_bf16 v[114:117], v[160:163], v[168:171], v[114:117]
	v_mfma_f32_16x16x32_bf16 v[102:105], v[152:155], v[176:179], v[102:105]
	v_mfma_f32_16x16x32_bf16 v[98:101], v[160:163], v[176:179], v[98:101]
	v_mfma_f32_16x16x32_bf16 v[86:89], v[152:155], v[196:199], v[86:89]
	v_mfma_f32_16x16x32_bf16 v[82:85], v[160:163], v[196:199], v[82:85]
	v_mfma_f32_16x16x32_bf16 v[70:73], v[152:155], v[204:207], v[70:73]
	v_mfma_f32_16x16x32_bf16 v[66:69], v[160:163], v[204:207], v[66:69]
	v_mfma_f32_16x16x32_bf16 v[118:121], v[156:159], v[172:175], v[118:121]
	v_mfma_f32_16x16x32_bf16 v[114:117], v[164:167], v[172:175], v[114:117]
	v_mfma_f32_16x16x32_bf16 v[102:105], v[156:159], v[192:195], v[102:105]
	v_mfma_f32_16x16x32_bf16 v[98:101], v[164:167], v[192:195], v[98:101]
	v_mfma_f32_16x16x32_bf16 v[86:89], v[156:159], v[200:203], v[86:89]
	v_mfma_f32_16x16x32_bf16 v[82:85], v[164:167], v[200:203], v[82:85]
	v_mfma_f32_16x16x32_bf16 v[70:73], v[156:159], v[208:211], v[70:73]
	v_mfma_f32_16x16x32_bf16 v[66:69], v[164:167], v[208:211], v[66:69]
	s_setprio 0
	s_barrier
; #define PG8_STAGE(bufoff, gbase, voff) do { _Pragma("unroll") for (int _i = 0; _i < 2; ++_i) \
;         __builtin_amdgcn_global_load_lds((const unsigned*)((const char*)(gbase) + (voff)[_i]), (PG8_LAS unsigned*)(lds + (bufoff) + ldsw + _i * 8192), 16, 0, 0); } while (0)
; #define PG8_LDA(dst, b, h) do { _Pragma("unroll") for (int m = 0; m < 4; ++m) _Pragma("unroll") for (int k = 0; k < 2; ++k) dst[m][k] = *(const PG8_LAS bf16x8*)(lds + PG8_SA(b, h) + aoff + m * 2048 + k * 1024); } while (0)
; #define PG8_MMA(ai, bj, At, Bt) do { __builtin_amdgcn_s_setprio(1); _Pragma("unroll") for (int m = 0; m < 4; ++m) _Pragma("unroll") for (int n = 0; n < 2; ++n) _Pragma("unroll") for (int k = 0; k < 2; ++k) \
;         acc[ai][bj][m][n] = __builtin_amdgcn_mfma_f32_16x16x32_bf16(Bt[n][k], At[m][k], acc[ai][bj][m][n], 0, 0, 0); __builtin_amdgcn_s_setprio(0); } while (0)
; #define PG8_WAIT_V(n) asm volatile("s_waitcnt vmcnt(" #n ")" ::: "memory")
; #define PG8_WAIT_L(n) asm volatile("s_waitcnt lgkmcnt(" #n ")" ::: "memory")
; #define PG8_BAR __builtin_amdgcn_s_barrier()
; #define PG8_SCHED __builtin_amdgcn_sched_barrier(0)
;     __device__ __forceinline__ void operator()(const f32x4 (&acc)[2][2][4][2], const Unit& u, int wr, int wc, int fr, int fq) const {
;     ...
;         for (int ai = 0; ai < 2; ++ai) {
;             u32x2e hw[4][2][2], pw[4][2][2]; float scv[4];
; #pragma unroll
;             for (int m = 0; m < 4; ++m) { const int row = row0 + ai * HALF + m * 16; const size_t ro = (size_t)row * 2048 + col0;
;                 scv[m] = GATE ? rss_in[row] : 0.f;
; #pragma unroll
;                 for (int bj = 0; bj < 2; ++bj)
; #pragma unroll
;                     for (int n = 0; n < 2; ++n) { const size_t p = ro + bj * HALF + n * 16; hw[m][bj][n] = *(const u32x2e*)(Hin + p); if (GATE) pw[m][bj][n] = *(const u32x2e*)(PP + p); else pw[m][bj][n] = (u32x2e){0u, 0u}; } }
; template <class Epi, class Sched, bool ALIGN_EPI = false, bool SP2 = false>
; __device__ __forceinline__ void gemm_phase(PG8_LAS unsigned char* lds, const Gemm g, const Sched& S, const Epi& E, const int tid) {
;     ...
;             PG8_LDA(At, 1, 1); PG8_STAGE(PG8_SB(1, 0), b3, voffB); PG8_STAGE(PG8_SB(1, 1), b3 + hstep, voffB); PG8_STAGE(PG8_SA(1, 0), a3, voffA);
;             PG8_WAIT_V(8); PG8_WAIT_L(0); PG8_BAR; PG8_MMA(1, 0, At, B0); PG8_MMA(1, 1, At, B1); PG8_BAR; PG8_SCHED;
	s_add_i32 s2, s30, s16
	v_lshl_add_u64 v[180:181], v[180:181], 0, s[24:25]
	s_mov_b32 m0, s2
	ds_read_b128 v[168:171], v238 offset:49152
	ds_read_b128 v[172:175], v238 offset:50176
	ds_read_b128 v[176:179], v238 offset:51200
	ds_read_b128 v[192:195], v238 offset:52224
	ds_read_b128 v[196:199], v238 offset:53248
	ds_read_b128 v[200:203], v238 offset:54272
	ds_read_b128 v[204:207], v238 offset:55296
	ds_read_b128 v[208:211], v238 offset:56320
	global_load_lds_dwordx4 v[180:181], off
	s_add_i32 m0, s2, 0x2000
	s_add_u32 s0, s0, 0x80080
	v_lshl_add_u64 v[180:181], v[212:213], 0, s[24:25]
	s_addc_u32 s1, s1, 0
	s_add_i32 s2, s31, s16
	global_load_lds_dwordx4 v[180:181], off
	v_lshl_add_u64 v[180:181], s[0:1], 0, v[0:1]
	s_mov_b32 m0, s2
	s_nop 0
	global_load_lds_dwordx4 v[180:181], off
	v_lshl_add_u64 v[180:181], s[0:1], 0, v[130:131]
	s_add_i32 m0, s2, 0x2000
	s_nop 0
	global_load_lds_dwordx4 v[180:181], off
	v_lshl_add_u64 v[180:181], v[222:223], 0, s[24:25]
	s_mov_b32 m0, s19
	s_nop 0
	global_load_lds_dwordx4 v[180:181], off
	v_lshl_add_u64 v[180:181], v[226:227], 0, s[24:25]
	s_mov_b32 m0, s20
	s_nop 0
	global_load_lds_dwordx4 v[180:181], off
	s_waitcnt vmcnt(8)
	s_waitcnt lgkmcnt(0)
	s_barrier
	s_setprio 1
	s_waitcnt lgkmcnt(0)
	v_mfma_f32_16x16x32_bf16 v[62:65], v[136:139], v[168:171], v[62:65]
	v_mfma_f32_16x16x32_bf16 v[58:61], v[144:147], v[168:171], v[58:61]
	v_mfma_f32_16x16x32_bf16 v[46:49], v[136:139], v[176:179], v[46:49]
	v_mfma_f32_16x16x32_bf16 v[42:45], v[144:147], v[176:179], v[42:45]
	v_mfma_f32_16x16x32_bf16 v[30:33], v[136:139], v[196:199], v[30:33]
	v_mfma_f32_16x16x32_bf16 v[26:29], v[144:147], v[196:199], v[26:29]
	v_mfma_f32_16x16x32_bf16 v[14:17], v[136:139], v[204:207], v[14:17]
	v_mfma_f32_16x16x32_bf16 v[10:13], v[144:147], v[204:207], v[10:13]
	v_mfma_f32_16x16x32_bf16 v[62:65], v[140:143], v[172:175], v[62:65]
	v_mfma_f32_16x16x32_bf16 v[58:61], v[148:151], v[172:175], v[58:61]
	v_mfma_f32_16x16x32_bf16 v[46:49], v[140:143], v[192:195], v[46:49]
	v_mfma_f32_16x16x32_bf16 v[42:45], v[148:151], v[192:195], v[42:45]
	v_mfma_f32_16x16x32_bf16 v[30:33], v[140:143], v[200:203], v[30:33]
	v_mfma_f32_16x16x32_bf16 v[26:29], v[148:151], v[200:203], v[26:29]
	v_mfma_f32_16x16x32_bf16 v[14:17], v[140:143], v[208:211], v[14:17]
	v_mfma_f32_16x16x32_bf16 v[10:13], v[148:151], v[208:211], v[10:13]
	s_setprio 0
	s_setprio 1
	v_mfma_f32_16x16x32_bf16 v[54:57], v[152:155], v[168:171], v[54:57]
	v_mfma_f32_16x16x32_bf16 v[50:53], v[160:163], v[168:171], v[50:53]
	v_mfma_f32_16x16x32_bf16 v[38:41], v[152:155], v[176:179], v[38:41]
	v_mfma_f32_16x16x32_bf16 v[34:37], v[160:163], v[176:179], v[34:37]
	v_mfma_f32_16x16x32_bf16 v[22:25], v[152:155], v[196:199], v[22:25]
	v_mfma_f32_16x16x32_bf16 v[18:21], v[160:163], v[196:199], v[18:21]
	v_mfma_f32_16x16x32_bf16 v[6:9], v[152:155], v[204:207], v[6:9]
	v_mfma_f32_16x16x32_bf16 v[2:5], v[160:163], v[204:207], v[2:5]
	v_mfma_f32_16x16x32_bf16 v[54:57], v[156:159], v[172:175], v[54:57]
	v_mfma_f32_16x16x32_bf16 v[50:53], v[164:167], v[172:175], v[50:53]
	v_mfma_f32_16x16x32_bf16 v[38:41], v[156:159], v[192:195], v[38:41]
	v_mfma_f32_16x16x32_bf16 v[34:37], v[164:167], v[192:195], v[34:37]
	v_mfma_f32_16x16x32_bf16 v[22:25], v[156:159], v[200:203], v[22:25]
	v_mfma_f32_16x16x32_bf16 v[18:21], v[164:167], v[200:203], v[18:21]
	v_mfma_f32_16x16x32_bf16 v[6:9], v[156:159], v[208:211], v[6:9]
	v_mfma_f32_16x16x32_bf16 v[2:5], v[164:167], v[208:211], v[2:5]
	s_setprio 0
	s_barrier
	s_add_i32 s29, s29, 2
	s_add_u32 s8, s8, 0x100
	s_addc_u32 s9, s9, 0
	s_add_u32 s27, s27, 0x100
	s_addc_u32 s28, s28, 0
	s_cmp_gt_u32 s29, 29
	s_cbranch_scc0 .LBB0_44
	s_cmpk_gt_u32 s13, 0xff
	s_cbranch_scc1 .Lepi3_noalign
	s_barrier
.Lepi3_noalign:
	s_waitcnt vmcnt(0)
	s_barrier
	v_lshlrev_b32_e32 v130, 9, v235
	v_lshrrev_b32_e32 v131, 3, v237
	v_and_b32_e32 v132, 15, v235
	v_xor_b32_e32 v131, v131, v132
	v_lshl_add_u32 v130, v131, 4, v130
	v_bfe_u32 v131, v237, 2, 1
	v_lshl_add_u32 v130, v131, 3, v130
	v_xor_b32_e32 v131, 32, v130
	v_add_u32_e32 v132, 0x10000, v130
	v_add_u32_e32 v133, 0x10000, v131
	v_lshrrev_b32_e32 v134, 5, v216
	v_and_b32_e32 v135, 31, v216
	v_xor_b32_e32 v135, v135, v134
	v_lshlrev_b32_e32 v135, 4, v135
	v_lshl_or_b32 v134, v134, 12, v135
	v_lshrrev_b32_e32 v135, 6, v183
	s_nop 0
	v_readfirstlane_b32 s7, v135
	s_lshl_b32 s8, s4, 20
	s_lshl_b32 s9, s6, 9
	s_add_i32 s8, s8, s9
	s_lshl_b32 s9, s7, 16
	s_add_i32 s8, s8, s9
	s_lshl_b32 s7, s7, 13
	s_add_u32 s10, s46, s8
	s_addc_u32 s11, s47, 0
	s_add_u32 s14, s52, s8
	s_addc_u32 s15, s53, 0
	s_add_i32 m0, s7, 0x0
	s_add_u32 s2, s10, 0x0
	s_addc_u32 s3, s11, 0
	v_xor_b32_e32 v135, 0x0, v134
	global_load_lds_dwordx4 v135, s[2:3]
	s_add_i32 m0, s7, 0x400
	s_add_u32 s2, s10, 0x2000
	s_addc_u32 s3, s11, 0
	v_xor_b32_e32 v135, 0x20, v134
	global_load_lds_dwordx4 v135, s[2:3]
	s_add_i32 m0, s7, 0x800
	s_add_u32 s2, s10, 0x4000
	s_addc_u32 s3, s11, 0
	v_xor_b32_e32 v135, 0x40, v134
	global_load_lds_dwordx4 v135, s[2:3]
	s_add_i32 m0, s7, 0xc00
	s_add_u32 s2, s10, 0x6000
	s_addc_u32 s3, s11, 0
	v_xor_b32_e32 v135, 0x60, v134
	global_load_lds_dwordx4 v135, s[2:3]
	s_add_i32 m0, s7, 0x1000
	s_add_u32 s2, s10, 0x8000
	s_addc_u32 s3, s11, 0
	v_xor_b32_e32 v135, 0x80, v134
	global_load_lds_dwordx4 v135, s[2:3]
	s_add_i32 m0, s7, 0x1400
	s_add_u32 s2, s10, 0xa000
	s_addc_u32 s3, s11, 0
	v_xor_b32_e32 v135, 0xa0, v134
	global_load_lds_dwordx4 v135, s[2:3]
	s_add_i32 m0, s7, 0x1800
	s_add_u32 s2, s10, 0xc000
	s_addc_u32 s3, s11, 0
	v_xor_b32_e32 v135, 0xc0, v134
	global_load_lds_dwordx4 v135, s[2:3]
	s_add_i32 m0, s7, 0x1c00
	s_add_u32 s2, s10, 0xe000
	s_addc_u32 s3, s11, 0
	v_xor_b32_e32 v135, 0xe0, v134
	global_load_lds_dwordx4 v135, s[2:3]
	s_add_i32 m0, s7, 0x10000
	s_add_u32 s2, s14, 0x0
	s_addc_u32 s3, s15, 0
	v_xor_b32_e32 v135, 0x0, v134
	global_load_lds_dwordx4 v135, s[2:3]
	s_add_i32 m0, s7, 0x10400
	s_add_u32 s2, s14, 0x2000
	s_addc_u32 s3, s15, 0
	v_xor_b32_e32 v135, 0x20, v134
	global_load_lds_dwordx4 v135, s[2:3]
	s_add_i32 m0, s7, 0x10800
	s_add_u32 s2, s14, 0x4000
	s_addc_u32 s3, s15, 0
	v_xor_b32_e32 v135, 0x40, v134
	global_load_lds_dwordx4 v135, s[2:3]
	s_add_i32 m0, s7, 0x10c00
	s_add_u32 s2, s14, 0x6000
	s_addc_u32 s3, s15, 0
	v_xor_b32_e32 v135, 0x60, v134
	global_load_lds_dwordx4 v135, s[2:3]
	s_add_i32 m0, s7, 0x11000
	s_add_u32 s2, s14, 0x8000
	s_addc_u32 s3, s15, 0
	v_xor_b32_e32 v135, 0x80, v134
	global_load_lds_dwordx4 v135, s[2:3]
	s_add_i32 m0, s7, 0x11400
	s_add_u32 s2, s14, 0xa000
	s_addc_u32 s3, s15, 0
	v_xor_b32_e32 v135, 0xa0, v134
	global_load_lds_dwordx4 v135, s[2:3]
	s_add_i32 m0, s7, 0x11800
	s_add_u32 s2, s14, 0xc000
	s_addc_u32 s3, s15, 0
	v_xor_b32_e32 v135, 0xc0, v134
	global_load_lds_dwordx4 v135, s[2:3]
	s_add_i32 m0, s7, 0x11c00
	s_add_u32 s2, s14, 0xe000
	s_addc_u32 s3, s15, 0
	v_xor_b32_e32 v135, 0xe0, v134
	global_load_lds_dwordx4 v135, s[2:3]
	s_waitcnt vmcnt(0)
	s_barrier
;     __device__ __forceinline__ void operator()(const f32x4 (&acc)[2][2][4][2], const Unit& u, int wr, int wc, int fr, int fq) const {
;         const int row0 = u.pm * BM + wr * 64 + fr, col0 = u.pn * BM + wc * 32 + 4 * fq;
; #pragma unroll
;         for (int ai = 0; ai < 2; ++ai) {
;             u32x2e hw[4][2][2], pw[4][2][2]; float scv[4];
; #pragma unroll
;             for (int m = 0; m < 4; ++m) { const int row = row0 + ai * HALF + m * 16; const size_t ro = (size_t)row * 2048 + col0;
;                 scv[m] = GATE ? rss_in[row] : 0.f;
; #pragma unroll
;                 for (int bj = 0; bj < 2; ++bj)
; #pragma unroll
;                     for (int n = 0; n < 2; ++n) { const size_t p = ro + bj * HALF + n * 16; hw[m][bj][n] = *(const u32x2e*)(Hin + p); if (GATE) pw[m][bj][n] = *(const u32x2e*)(PP + p); else pw[m][bj][n] = (u32x2e){0u, 0u}; } }
; #pragma unroll
;             for (int m = 0; m < 4; ++m) { const int row = row0 + ai * HALF + m * 16; const size_t ro = (size_t)row * 2048 + col0;
;                 float sc = 1.f; if (GATE) sc = rsqrtf(scv[m] * (1.f / 2048.f) + 1e-6f);
	v_lshl_add_u32 v138, s4, 8, v235
	v_lshl_or_b32 v136, s6, 8, v237
	v_ashrrev_i32_e32 v139, 31, v138
	v_ashrrev_i32_e32 v137, 31, v136
	v_lshlrev_b64 v[140:141], 11, v[138:139]
	v_lshl_add_u64 v[142:143], v[140:141], 0, v[136:137]
	v_lshl_add_u64 v[140:141], v[138:139], 2, s[54:55]
	v_lshlrev_b64 v[142:143], 1, v[142:143]
	v_lshl_add_u64 v[144:145], s[46:47], 0, v[142:143]
	global_load_dword v250, v[140:141], off
	ds_read_b64 v[242:243], v130 offset:0
	v_lshl_add_u64 v[144:145], s[52:53], 0, v[142:143]
	v_or_b32_e32 v146, 32, v142
	v_mov_b32_e32 v147, v143
	v_or_b32_e32 v150, 0x100, v142
	v_mov_b32_e32 v151, v143
	v_lshl_add_u64 v[148:149], s[46:47], 0, v[146:147]
	v_lshl_add_u64 v[146:147], s[52:53], 0, v[146:147]
	v_lshl_add_u64 v[152:153], s[46:47], 0, v[150:151]
	ds_read_b64 v[244:245], v132 offset:0
	ds_read_b64 v[246:247], v131 offset:0
	ds_read_b64 v[248:249], v133 offset:0
	ds_read_b64 v[212:213], v130 offset:256
	v_or_b32_e32 v204, 16, v138
	v_ashrrev_i32_e32 v205, 31, v204
	v_lshlrev_b64 v[148:149], 11, v[204:205]
	v_lshl_add_u64 v[148:149], v[148:149], 0, v[136:137]
	v_lshl_add_u64 v[144:145], s[52:53], 0, v[150:151]
	v_or_b32_e32 v142, 0x120, v142
	v_lshlrev_b64 v[148:149], 1, v[148:149]
	v_lshl_add_u64 v[146:147], s[46:47], 0, v[142:143]
	v_lshl_add_u64 v[142:143], s[52:53], 0, v[142:143]
	v_lshl_add_u64 v[150:151], s[46:47], 0, v[148:149]
	ds_read_b64 v[210:211], v132 offset:256
	ds_read_b64 v[208:209], v131 offset:256
	ds_read_b64 v[206:207], v133 offset:256
	ds_read_b64 v[202:203], v130 offset:8192
	v_or_b32_e32 v144, 32, v148
	v_mov_b32_e32 v145, v149
	v_or_b32_e32 v176, 32, v138
	v_lshl_add_u64 v[142:143], s[52:53], 0, v[148:149]
	v_lshl_add_u64 v[146:147], s[46:47], 0, v[144:145]
	v_lshl_add_u64 v[144:145], s[52:53], 0, v[144:145]
	v_or_b32_e32 v150, 0x100, v148
	v_mov_b32_e32 v151, v149
	v_or_b32_e32 v148, 0x120, v148
	v_ashrrev_i32_e32 v177, 31, v176
	v_lshl_add_u64 v[152:153], s[46:47], 0, v[150:151]
	ds_read_b64 v[200:201], v132 offset:8192
	ds_read_b64 v[198:199], v131 offset:8192
	ds_read_b64 v[196:197], v133 offset:8192
	ds_read_b64 v[194:195], v130 offset:8448
	v_lshl_add_u64 v[144:145], s[46:47], 0, v[148:149]
	v_lshl_add_u64 v[146:147], s[52:53], 0, v[148:149]
	v_lshlrev_b64 v[148:149], 11, v[176:177]
	v_lshl_add_u64 v[148:149], v[148:149], 0, v[136:137]
	v_lshl_add_u64 v[142:143], s[52:53], 0, v[150:151]
	v_lshlrev_b64 v[148:149], 1, v[148:149]
	v_lshl_add_u64 v[150:151], s[46:47], 0, v[148:149]
	ds_read_b64 v[192:193], v132 offset:8448
	ds_read_b64 v[180:181], v131 offset:8448
	ds_read_b64 v[178:179], v133 offset:8448
	ds_read_b64 v[174:175], v130 offset:16384
	v_or_b32_e32 v144, 32, v148
	v_mov_b32_e32 v145, v149
	v_or_b32_e32 v158, 48, v138
	v_lshl_add_u64 v[142:143], s[52:53], 0, v[148:149]
	v_lshl_add_u64 v[146:147], s[46:47], 0, v[144:145]
	v_lshl_add_u64 v[144:145], s[52:53], 0, v[144:145]
	v_or_b32_e32 v150, 0x100, v148
	v_mov_b32_e32 v151, v149
	v_or_b32_e32 v148, 0x120, v148
	v_ashrrev_i32_e32 v159, 31, v158
	v_lshl_add_u64 v[152:153], s[46:47], 0, v[150:151]
	ds_read_b64 v[172:173], v132 offset:16384
	ds_read_b64 v[170:171], v131 offset:16384
	ds_read_b64 v[168:169], v133 offset:16384
	ds_read_b64 v[166:167], v130 offset:16640
	v_lshl_add_u64 v[144:145], s[46:47], 0, v[148:149]
	v_lshl_add_u64 v[146:147], s[52:53], 0, v[148:149]
	v_lshlrev_b64 v[148:149], 11, v[158:159]
	v_lshl_add_u64 v[148:149], v[148:149], 0, v[136:137]
	v_lshl_add_u64 v[142:143], s[52:53], 0, v[150:151]
	v_lshlrev_b64 v[226:227], 1, v[148:149]
	global_load_dword v241, v[140:141], off offset:64
	global_load_dword v240, v[140:141], off offset:128
	global_load_dword v239, v[140:141], off offset:192
	v_lshl_add_u64 v[148:149], s[46:47], 0, v[226:227]
	ds_read_b64 v[164:165], v132 offset:16640
	ds_read_b64 v[162:163], v131 offset:16640
	ds_read_b64 v[160:161], v133 offset:16640
	ds_read_b64 v[156:157], v130 offset:24576
	v_or_b32_e32 v144, 32, v226
	v_mov_b32_e32 v145, v227
	v_or_b32_e32 v222, 0x100, v226
	v_mov_b32_e32 v223, v227
	v_lshl_add_u64 v[142:143], s[52:53], 0, v[226:227]
	v_lshl_add_u64 v[146:147], s[46:47], 0, v[144:145]
	v_lshl_add_u64 v[148:149], s[46:47], 0, v[222:223]
	v_lshl_add_u64 v[144:145], s[52:53], 0, v[144:145]
	ds_read_b64 v[154:155], v132 offset:24576
	ds_read_b64 v[152:153], v131 offset:24576
	ds_read_b64 v[150:151], v133 offset:24576
	s_nop 0
	ds_read_b64 v[148:149], v130 offset:24832
	v_or_b32_e32 v226, 0x120, v226
	v_lshl_add_u64 v[142:143], s[52:53], 0, v[222:223]
	v_lshl_add_u64 v[144:145], s[46:47], 0, v[226:227]
	v_lshl_add_u64 v[222:223], s[52:53], 0, v[226:227]
	s_waitcnt vmcnt(0) lgkmcnt(0)
	v_fmamk_f32 v146, v250, 0x3a000000, v214
	v_mul_f32_e32 v147, 0x4b800000, v146
	v_cmp_gt_f32_e32 vcc, s65, v146
	v_lshlrev_b32_e32 v227, 16, v242
	v_and_b32_e32 v242, 0xffff0000, v242
	v_cndmask_b32_e32 v146, v146, v147, vcc
	v_rsq_f32_e32 v226, v146
	ds_read_b64 v[146:147], v132 offset:24832
	s_nop 0
	ds_read_b64 v[144:145], v131 offset:24832
	s_nop 0
	ds_read_b64 v[142:143], v133 offset:24832
	s_waitcnt vmcnt(0) lgkmcnt(0)
; __device__ __forceinline__ unsigned cvt_pk_bf16(float lo, float hi) { unsigned r; asm volatile("v_cvt_pk_bf16_f32 %0, %1, %2" : "=v"(r) : "v"(lo), "v"(hi)); return r; }
;     __device__ __forceinline__ void operator()(const f32x4 (&acc)[2][2][4][2], const Unit& u, int wr, int wc, int fr, int fq) const {
;     ...
;             for (int m = 0; m < 4; ++m) { const int row = row0 + ai * HALF + m * 16; const size_t ro = (size_t)row * 2048 + col0;
;                 float sc = 1.f; if (GATE) sc = rsqrtf(scv[m] * (1.f / 2048.f) + 1e-6f);
;                 float s = 0.f;
; #pragma unroll
;                 for (int bj = 0; bj < 2; ++bj)
; #pragma unroll
;                     for (int n = 0; n < 2; ++n) { const size_t p = ro + bj * HALF + n * 16; const u32x2e hh = hw[m][bj][n], pp = pw[m][bj][n]; const f32x4 a = acc[ai][bj][m][n];
;                         f32x4 h; h[0] = __uint_as_float(hh.x << 16); h[1] = __uint_as_float(hh.x & 0xffff0000u); h[2] = __uint_as_float(hh.y << 16); h[3] = __uint_as_float(hh.y & 0xffff0000u);
;                         if (GATE) {
;                             h[0] += __builtin_amdgcn_rcpf(1.f + __expf(-sc * a[0])) * __uint_as_float(pp.x << 16); h[1] += __builtin_amdgcn_rcpf(1.f + __expf(-sc * a[1])) * __uint_as_float(pp.x & 0xffff0000u);
;                             h[2] += __builtin_amdgcn_rcpf(1.f + __expf(-sc * a[2])) * __uint_as_float(pp.y << 16); h[3] += __builtin_amdgcn_rcpf(1.f + __expf(-sc * a[3])) * __uint_as_float(pp.y & 0xffff0000u); }
;                         else h = h + a;
;                         s += (h[0] * h[0] + h[1] * h[1]) + (h[2] * h[2] + h[3] * h[3]);
;                         u32x2e o; o.x = cvt_pk_bf16(h[0], h[1]); o.y = cvt_pk_bf16(h[2], h[3]); *(u32x2e*)(Hout + p) = o; }
;                 s += __shfl_xor(s, 16); s += __shfl_xor(s, 32);
;                 if (fq == 0) atomicAdd(rss_out + row, s); }
	v_lshlrev_b32_e32 v225, 16, v244
	v_lshlrev_b32_e32 v250, 16, v243
	v_mul_f32_e32 v222, 0x45800000, v226
	v_cndmask_b32_e32 v226, v226, v222, vcc
	v_mul_f32_e64 v126, v126, -v226
	v_mul_f32_e32 v126, 0x3fb8aa3b, v126
	v_exp_f32_e32 v126, v126
	v_mul_f32_e64 v127, v127, -v226
	v_mul_f32_e32 v127, 0x3fb8aa3b, v127
	v_exp_f32_e32 v127, v127
	v_add_f32_e32 v126, 1.0, v126
	v_rcp_f32_e32 v126, v126
	v_mul_f32_e64 v128, v128, -v226
	v_mul_f32_e32 v128, 0x3fb8aa3b, v128
	v_mul_f32_e64 v129, v129, -v226
	v_fmac_f32_e32 v227, v126, v225
	v_add_f32_e32 v126, 1.0, v127
	v_rcp_f32_e32 v126, v126
	v_exp_f32_e32 v128, v128
	v_mul_f32_e32 v129, 0x3fb8aa3b, v129
	v_exp_f32_e32 v129, v129
	v_and_b32_e32 v127, 0xffff0000, v244
	v_fmac_f32_e32 v242, v126, v127
	v_add_f32_e32 v126, 1.0, v128
	v_mul_f32_e64 v122, v122, -v226
	v_rcp_f32_e32 v126, v126
	v_add_f32_e32 v127, 1.0, v129
	v_mul_f32_e32 v122, 0x3fb8aa3b, v122
	v_rcp_f32_e32 v127, v127
	v_exp_f32_e32 v122, v122
	v_lshlrev_b32_e32 v128, 16, v245
	v_and_b32_e32 v243, 0xffff0000, v243
	v_fmac_f32_e32 v250, v126, v128
	v_and_b32_e32 v126, 0xffff0000, v245
	v_mul_f32_e64 v123, v123, -v226
	v_fmac_f32_e32 v243, v127, v126
	v_add_f32_e32 v122, 1.0, v122
	v_mul_f32_e32 v123, 0x3fb8aa3b, v123
	v_lshlrev_b64 v[222:223], 12, v[138:139]
	v_mul_f32_e32 v126, v242, v242
	v_mul_f32_e32 v127, v243, v243
	v_rcp_f32_e32 v122, v122
	v_exp_f32_e32 v123, v123
	v_fmac_f32_e32 v126, v227, v227
	v_fmac_f32_e32 v127, v250, v250
	v_lshl_add_u64 v[128:129], s[48:49], 0, v[222:223]
	v_add_f32_e32 v225, v126, v127
	v_cvt_pk_bf16_f32 v126, v227, v242
	v_lshl_add_u64 v[128:129], v[136:137], 1, v[128:129]
	v_cvt_pk_bf16_f32 v127, v250, v243
	global_store_dwordx2 v[128:129], v[126:127], off
	v_lshlrev_b32_e32 v126, 16, v246
	v_lshlrev_b32_e32 v227, 16, v248
	v_mul_f32_e64 v124, v124, -v226
	v_fmac_f32_e32 v126, v122, v227
	v_add_f32_e32 v122, 1.0, v123
	v_mul_f32_e32 v124, 0x3fb8aa3b, v124
	v_mul_f32_e64 v125, v125, -v226
	v_rcp_f32_e32 v122, v122
	v_exp_f32_e32 v124, v124
	v_mul_f32_e32 v125, 0x3fb8aa3b, v125
	v_exp_f32_e32 v125, v125
	v_and_b32_e32 v127, 0xffff0000, v246
	v_and_b32_e32 v123, 0xffff0000, v248
	v_fmac_f32_e32 v127, v122, v123
	v_add_f32_e32 v122, 1.0, v124
	v_mul_f32_e64 v118, v118, -v226
	v_rcp_f32_e32 v122, v122
	v_add_f32_e32 v123, 1.0, v125
	v_mul_f32_e32 v118, 0x3fb8aa3b, v118
	v_rcp_f32_e32 v123, v123
	v_exp_f32_e32 v118, v118
	v_lshlrev_b32_e32 v222, 16, v247
	v_lshlrev_b32_e32 v124, 16, v249
	v_and_b32_e32 v223, 0xffff0000, v247
	v_fmac_f32_e32 v222, v122, v124
	v_and_b32_e32 v122, 0xffff0000, v249
	v_mul_f32_e64 v119, v119, -v226
	v_fmac_f32_e32 v223, v123, v122
	v_add_f32_e32 v118, 1.0, v118
	v_mul_f32_e32 v119, 0x3fb8aa3b, v119
	v_mul_f32_e32 v122, v127, v127
	v_mul_f32_e32 v123, v223, v223
	v_rcp_f32_e32 v118, v118
	v_exp_f32_e32 v119, v119
	v_fmac_f32_e32 v122, v126, v126
	v_fmac_f32_e32 v123, v222, v222
	v_add_f32_e32 v122, v122, v123
	v_add_f32_e32 v124, v225, v122
	v_cvt_pk_bf16_f32 v122, v126, v127
	v_lshlrev_b32_e32 v125, 16, v212
	v_and_b32_e32 v126, 0xffff0000, v212
	v_lshlrev_b32_e32 v127, 16, v213
	v_and_b32_e32 v212, 0xffff0000, v213
	v_lshlrev_b32_e32 v213, 16, v210
	v_mul_f32_e64 v120, v120, -v226
	v_fmac_f32_e32 v125, v118, v213
	v_add_f32_e32 v118, 1.0, v119
	v_mul_f32_e32 v120, 0x3fb8aa3b, v120
	v_mul_f32_e64 v121, v121, -v226
	v_rcp_f32_e32 v118, v118
	v_exp_f32_e32 v120, v120
	v_mul_f32_e32 v121, 0x3fb8aa3b, v121
	v_exp_f32_e32 v121, v121
	v_and_b32_e32 v119, 0xffff0000, v210
	v_mul_f32_e64 v114, v114, -v226
	v_fmac_f32_e32 v126, v118, v119
	v_add_f32_e32 v118, 1.0, v120
	v_mul_f32_e32 v114, 0x3fb8aa3b, v114
	v_rcp_f32_e32 v118, v118
	v_add_f32_e32 v119, 1.0, v121
	v_exp_f32_e32 v114, v114
	v_rcp_f32_e32 v119, v119
	v_lshlrev_b32_e32 v120, 16, v211
	v_mul_f32_e64 v115, v115, -v226
	v_fmac_f32_e32 v127, v118, v120
	v_and_b32_e32 v118, 0xffff0000, v211
	v_add_f32_e32 v114, 1.0, v114
	v_mul_f32_e32 v115, 0x3fb8aa3b, v115
	v_fmac_f32_e32 v212, v119, v118
	v_rcp_f32_e32 v114, v114
	v_exp_f32_e32 v115, v115
	v_mul_f32_e32 v118, v126, v126
	v_mul_f32_e32 v119, v212, v212
	v_fmac_f32_e32 v118, v125, v125
	v_fmac_f32_e32 v119, v127, v127
	v_add_f32_e32 v118, v118, v119
	v_lshlrev_b32_e32 v119, 16, v208
	v_and_b32_e32 v120, 0xffff0000, v208
	v_lshlrev_b32_e32 v208, 16, v206
	v_mul_f32_e64 v116, v116, -v226
	v_fmac_f32_e32 v119, v114, v208
	v_add_f32_e32 v114, 1.0, v115
	v_mul_f32_e32 v116, 0x3fb8aa3b, v116
	v_mul_f32_e64 v117, v117, -v226
	v_rcp_f32_e32 v114, v114
	v_exp_f32_e32 v116, v116
	v_mul_f32_e32 v117, 0x3fb8aa3b, v117
	v_exp_f32_e32 v117, v117
	v_and_b32_e32 v115, 0xffff0000, v206
	v_fmac_f32_e32 v120, v114, v115
	v_add_f32_e32 v114, 1.0, v116
	v_rcp_f32_e32 v114, v114
	v_add_f32_e32 v115, 1.0, v117
	v_rcp_f32_e32 v115, v115
	v_lshlrev_b32_e32 v121, 16, v209
	v_lshlrev_b32_e32 v116, 16, v207
	v_add_f32_e32 v118, v118, v124
	v_and_b32_e32 v124, 0xffff0000, v209
	v_fmac_f32_e32 v121, v114, v116
	v_and_b32_e32 v114, 0xffff0000, v207
	v_fmac_f32_e32 v124, v115, v114
	v_mul_f32_e32 v114, v120, v120
	v_mul_f32_e32 v115, v124, v124
	v_fmac_f32_e32 v114, v119, v119
	v_fmac_f32_e32 v115, v121, v121
	v_add_f32_e32 v114, v114, v115
	v_and_b32_e32 v115, 64, v216
	v_add_f32_e32 v116, v114, v118
	v_xor_b32_e32 v114, 16, v216
	v_add_u32_e32 v117, 64, v115
	v_cmp_lt_i32_e32 vcc, v114, v117
	v_cvt_pk_bf16_f32 v123, v222, v223
	global_store_dwordx2 v[128:129], v[122:123], off offset:32
	s_nop 0
	v_cndmask_b32_e32 v114, v216, v114, vcc
	v_lshlrev_b32_e32 v206, 2, v114
	ds_bpermute_b32 v118, v206, v116
	v_cvt_pk_bf16_f32 v114, v125, v126
	v_cvt_pk_bf16_f32 v115, v127, v212
	global_store_dwordx2 v[128:129], v[114:115], off offset:256
	v_xor_b32_e32 v114, 32, v216
	v_cmp_lt_i32_e32 vcc, v114, v117
	s_waitcnt lgkmcnt(0)
	v_add_f32_e32 v116, v116, v118
	v_cndmask_b32_e32 v114, v216, v114, vcc
	v_lshlrev_b32_e32 v207, 2, v114
	ds_bpermute_b32 v117, v207, v116
	v_cvt_pk_bf16_f32 v114, v119, v120
	v_cvt_pk_bf16_f32 v115, v121, v124
	global_store_dwordx2 v[128:129], v[114:115], off offset:288
	v_lshl_add_u64 v[114:115], v[138:139], 2, s[50:51]
	s_and_saveexec_b64 s[0:1], s[42:43]
	s_cbranch_execz .LBB0_47
	s_waitcnt lgkmcnt(0)
	v_add_f32_e32 v116, v116, v117
	global_atomic_add_f32 v[114:115], v116, off

;     __device__ __forceinline__ void operator()(const f32x4 (&acc)[2][2][4][2], const Unit& u, int wr, int wc, int fr, int fq) const {
;     ...
;         for (int ai = 0; ai < 2; ++ai) {
;             u32x2e hw[4][2][2], pw[4][2][2]; float scv[4];
; #pragma unroll
;             for (int m = 0; m < 4; ++m) { const int row = row0 + ai * HALF + m * 16; const size_t ro = (size_t)row * 2048 + col0;
;                 scv[m] = GATE ? rss_in[row] : 0.f;
; #pragma unroll
;                 for (int bj = 0; bj < 2; ++bj)
; #pragma unroll
;                     for (int n = 0; n < 2; ++n) { const size_t p = ro + bj * HALF + n * 16; hw[m][bj][n] = *(const u32x2e*)(Hin + p); if (GATE) pw[m][bj][n] = *(const u32x2e*)(PP + p); else pw[m][bj][n] = (u32x2e){0u, 0u}; } }
.LBB0_53:
	s_or_b64 exec, exec, s[0:1]
	s_waitcnt lgkmcnt(0)
	s_barrier
	s_add_i32 m0, s7, 0x0
	s_add_u32 s2, s10, 0x80000
	s_addc_u32 s3, s11, 0
	v_xor_b32_e32 v135, 0x0, v134
	global_load_lds_dwordx4 v135, s[2:3]
	s_add_i32 m0, s7, 0x400
	s_add_u32 s2, s10, 0x82000
	s_addc_u32 s3, s11, 0
	v_xor_b32_e32 v135, 0x20, v134
	global_load_lds_dwordx4 v135, s[2:3]
	s_add_i32 m0, s7, 0x800
	s_add_u32 s2, s10, 0x84000
	s_addc_u32 s3, s11, 0
	v_xor_b32_e32 v135, 0x40, v134
	global_load_lds_dwordx4 v135, s[2:3]
	s_add_i32 m0, s7, 0xc00
	s_add_u32 s2, s10, 0x86000
	s_addc_u32 s3, s11, 0
	v_xor_b32_e32 v135, 0x60, v134
	global_load_lds_dwordx4 v135, s[2:3]
	s_add_i32 m0, s7, 0x1000
	s_add_u32 s2, s10, 0x88000
	s_addc_u32 s3, s11, 0
	v_xor_b32_e32 v135, 0x80, v134
	global_load_lds_dwordx4 v135, s[2:3]
	s_add_i32 m0, s7, 0x1400
	s_add_u32 s2, s10, 0x8a000
	s_addc_u32 s3, s11, 0
	v_xor_b32_e32 v135, 0xa0, v134
	global_load_lds_dwordx4 v135, s[2:3]
	s_add_i32 m0, s7, 0x1800
	s_add_u32 s2, s10, 0x8c000
	s_addc_u32 s3, s11, 0
	v_xor_b32_e32 v135, 0xc0, v134
	global_load_lds_dwordx4 v135, s[2:3]
	s_add_i32 m0, s7, 0x1c00
	s_add_u32 s2, s10, 0x8e000
	s_addc_u32 s3, s11, 0
	v_xor_b32_e32 v135, 0xe0, v134
	global_load_lds_dwordx4 v135, s[2:3]
	s_add_i32 m0, s7, 0x10000
	s_add_u32 s2, s14, 0x80000
	s_addc_u32 s3, s15, 0
	v_xor_b32_e32 v135, 0x0, v134
	global_load_lds_dwordx4 v135, s[2:3]
	s_add_i32 m0, s7, 0x10400
	s_add_u32 s2, s14, 0x82000
	s_addc_u32 s3, s15, 0
	v_xor_b32_e32 v135, 0x20, v134
	global_load_lds_dwordx4 v135, s[2:3]
	s_add_i32 m0, s7, 0x10800
	s_add_u32 s2, s14, 0x84000
	s_addc_u32 s3, s15, 0
	v_xor_b32_e32 v135, 0x40, v134
	global_load_lds_dwordx4 v135, s[2:3]
	s_add_i32 m0, s7, 0x10c00
	s_add_u32 s2, s14, 0x86000
	s_addc_u32 s3, s15, 0
	v_xor_b32_e32 v135, 0x60, v134
	global_load_lds_dwordx4 v135, s[2:3]
	s_add_i32 m0, s7, 0x11000
	s_add_u32 s2, s14, 0x88000
	s_addc_u32 s3, s15, 0
	v_xor_b32_e32 v135, 0x80, v134
	global_load_lds_dwordx4 v135, s[2:3]
	s_add_i32 m0, s7, 0x11400
	s_add_u32 s2, s14, 0x8a000
	s_addc_u32 s3, s15, 0
	v_xor_b32_e32 v135, 0xa0, v134
	global_load_lds_dwordx4 v135, s[2:3]
	s_add_i32 m0, s7, 0x11800
	s_add_u32 s2, s14, 0x8c000
	s_addc_u32 s3, s15, 0
	v_xor_b32_e32 v135, 0xc0, v134
	global_load_lds_dwordx4 v135, s[2:3]
	s_add_i32 m0, s7, 0x11c00
	s_add_u32 s2, s14, 0x8e000
	s_addc_u32 s3, s15, 0
	v_xor_b32_e32 v135, 0xe0, v134
	global_load_lds_dwordx4 v135, s[2:3]
	s_waitcnt vmcnt(0)
	s_barrier
	v_add_u32_e32 v144, 0x80, v138
	v_ashrrev_i32_e32 v145, 31, v144
	s_waitcnt lgkmcnt(0)
	v_lshlrev_b64 v[66:67], 11, v[144:145]
	v_lshl_add_u64 v[66:67], v[66:67], 0, v[136:137]
	v_lshlrev_b64 v[66:67], 1, v[66:67]
	v_lshl_add_u64 v[68:69], s[46:47], 0, v[66:67]
	global_load_dword v143, v[140:141], off offset:512
	ds_read_b64 v[146:147], v130 offset:0
	v_lshl_add_u64 v[68:69], s[52:53], 0, v[66:67]
	v_or_b32_e32 v70, 32, v66
	v_mov_b32_e32 v71, v67
	v_or_b32_e32 v74, 0x100, v66
	v_mov_b32_e32 v75, v67
	v_lshl_add_u64 v[72:73], s[46:47], 0, v[70:71]
	v_lshl_add_u64 v[70:71], s[52:53], 0, v[70:71]
	v_lshl_add_u64 v[76:77], s[46:47], 0, v[74:75]
	ds_read_b64 v[148:149], v132 offset:0
	ds_read_b64 v[150:151], v131 offset:0
	ds_read_b64 v[152:153], v133 offset:0
	ds_read_b64 v[128:129], v130 offset:256
	v_add_u32_e32 v120, 0x90, v138
	v_ashrrev_i32_e32 v121, 31, v120
	v_lshlrev_b64 v[72:73], 11, v[120:121]
	v_lshl_add_u64 v[72:73], v[72:73], 0, v[136:137]
	v_lshl_add_u64 v[68:69], s[52:53], 0, v[74:75]
	v_or_b32_e32 v66, 0x120, v66
	v_lshlrev_b64 v[72:73], 1, v[72:73]
	v_lshl_add_u64 v[70:71], s[46:47], 0, v[66:67]
	v_lshl_add_u64 v[66:67], s[52:53], 0, v[66:67]
	v_lshl_add_u64 v[74:75], s[46:47], 0, v[72:73]
	ds_read_b64 v[126:127], v132 offset:256
	ds_read_b64 v[124:125], v131 offset:256
	ds_read_b64 v[122:123], v133 offset:256
	ds_read_b64 v[118:119], v130 offset:8192
	v_or_b32_e32 v68, 32, v72
	v_mov_b32_e32 v69, v73
	v_add_u32_e32 v100, 0xa0, v138
	v_lshl_add_u64 v[66:67], s[52:53], 0, v[72:73]
	v_lshl_add_u64 v[70:71], s[46:47], 0, v[68:69]
	v_lshl_add_u64 v[68:69], s[52:53], 0, v[68:69]
	v_or_b32_e32 v74, 0x100, v72
	v_mov_b32_e32 v75, v73
	v_or_b32_e32 v72, 0x120, v72
	v_ashrrev_i32_e32 v101, 31, v100
	v_lshl_add_u64 v[76:77], s[46:47], 0, v[74:75]
	ds_read_b64 v[116:117], v132 offset:8192
	ds_read_b64 v[112:113], v131 offset:8192
	ds_read_b64 v[110:111], v133 offset:8192
	ds_read_b64 v[108:109], v130 offset:8448
	v_lshl_add_u64 v[68:69], s[46:47], 0, v[72:73]
	v_lshl_add_u64 v[70:71], s[52:53], 0, v[72:73]
	v_lshlrev_b64 v[72:73], 11, v[100:101]
	v_lshl_add_u64 v[72:73], v[72:73], 0, v[136:137]
	v_lshl_add_u64 v[66:67], s[52:53], 0, v[74:75]
	v_lshlrev_b64 v[72:73], 1, v[72:73]
	v_lshl_add_u64 v[74:75], s[46:47], 0, v[72:73]
	ds_read_b64 v[106:107], v132 offset:8448
	ds_read_b64 v[104:105], v131 offset:8448
	ds_read_b64 v[102:103], v133 offset:8448
	ds_read_b64 v[98:99], v130 offset:16384
	v_or_b32_e32 v68, 32, v72
	v_mov_b32_e32 v69, v73
	v_add_u32_e32 v82, 0xb0, v138
	v_lshl_add_u64 v[66:67], s[52:53], 0, v[72:73]
	v_lshl_add_u64 v[70:71], s[46:47], 0, v[68:69]
	v_lshl_add_u64 v[68:69], s[52:53], 0, v[68:69]
	v_or_b32_e32 v74, 0x100, v72
	v_mov_b32_e32 v75, v73
	v_or_b32_e32 v72, 0x120, v72
	v_ashrrev_i32_e32 v83, 31, v82
	v_lshl_add_u64 v[76:77], s[46:47], 0, v[74:75]
	ds_read_b64 v[96:97], v132 offset:16384
	ds_read_b64 v[94:95], v131 offset:16384
	ds_read_b64 v[92:93], v133 offset:16384
	ds_read_b64 v[90:91], v130 offset:16640
	v_lshl_add_u64 v[68:69], s[46:47], 0, v[72:73]
	v_lshl_add_u64 v[70:71], s[52:53], 0, v[72:73]
	v_lshlrev_b64 v[72:73], 11, v[82:83]
	v_lshl_add_u64 v[72:73], v[72:73], 0, v[136:137]
	v_lshl_add_u64 v[66:67], s[52:53], 0, v[74:75]
	global_load_dword v142, v[140:141], off offset:576
	global_load_dword v139, v[140:141], off offset:640
	global_load_dword v138, v[140:141], off offset:704
	v_lshlrev_b64 v[140:141], 1, v[72:73]
	v_lshl_add_u64 v[72:73], s[46:47], 0, v[140:141]
	ds_read_b64 v[88:89], v132 offset:16640
	ds_read_b64 v[86:87], v131 offset:16640
	ds_read_b64 v[84:85], v133 offset:16640
	ds_read_b64 v[80:81], v130 offset:24576
	v_or_b32_e32 v68, 32, v140
	v_mov_b32_e32 v69, v141
	v_or_b32_e32 v154, 0x100, v140
	v_mov_b32_e32 v155, v141
	v_lshl_add_u64 v[66:67], s[52:53], 0, v[140:141]
	v_lshl_add_u64 v[70:71], s[46:47], 0, v[68:69]
	v_lshl_add_u64 v[72:73], s[46:47], 0, v[154:155]
	v_lshl_add_u64 v[68:69], s[52:53], 0, v[68:69]
	ds_read_b64 v[78:79], v132 offset:24576
	ds_read_b64 v[76:77], v131 offset:24576
	ds_read_b64 v[74:75], v133 offset:24576
	s_nop 0
	ds_read_b64 v[72:73], v130 offset:24832
	v_or_b32_e32 v140, 0x120, v140
	v_lshl_add_u64 v[66:67], s[52:53], 0, v[154:155]
	v_lshl_add_u64 v[68:69], s[46:47], 0, v[140:141]
	v_lshl_add_u64 v[140:141], s[52:53], 0, v[140:141]
	s_waitcnt vmcnt(0) lgkmcnt(0)
; __device__ __forceinline__ unsigned cvt_pk_bf16(float lo, float hi) { unsigned r; asm volatile("v_cvt_pk_bf16_f32 %0, %1, %2" : "=v"(r) : "v"(lo), "v"(hi)); return r; }
;     __device__ __forceinline__ void operator()(const f32x4 (&acc)[2][2][4][2], const Unit& u, int wr, int wc, int fr, int fq) const {
;     ...
;             for (int m = 0; m < 4; ++m) { const int row = row0 + ai * HALF + m * 16; const size_t ro = (size_t)row * 2048 + col0;
;                 float sc = 1.f; if (GATE) sc = rsqrtf(scv[m] * (1.f / 2048.f) + 1e-6f);
;                 float s = 0.f;
; #pragma unroll
;                 for (int bj = 0; bj < 2; ++bj)
; #pragma unroll
;                     for (int n = 0; n < 2; ++n) { const size_t p = ro + bj * HALF + n * 16; const u32x2e hh = hw[m][bj][n], pp = pw[m][bj][n]; const f32x4 a = acc[ai][bj][m][n];
;                         f32x4 h; h[0] = __uint_as_float(hh.x << 16); h[1] = __uint_as_float(hh.x & 0xffff0000u); h[2] = __uint_as_float(hh.y << 16); h[3] = __uint_as_float(hh.y & 0xffff0000u);
;                         if (GATE) {
;                             h[0] += __builtin_amdgcn_rcpf(1.f + __expf(-sc * a[0])) * __uint_as_float(pp.x << 16); h[1] += __builtin_amdgcn_rcpf(1.f + __expf(-sc * a[1])) * __uint_as_float(pp.x & 0xffff0000u);
;                             h[2] += __builtin_amdgcn_rcpf(1.f + __expf(-sc * a[2])) * __uint_as_float(pp.y << 16); h[3] += __builtin_amdgcn_rcpf(1.f + __expf(-sc * a[3])) * __uint_as_float(pp.y & 0xffff0000u); }
;                         else h = h + a;
;                         s += (h[0] * h[0] + h[1] * h[1]) + (h[2] * h[2] + h[3] * h[3]);
;                         u32x2e o; o.x = cvt_pk_bf16(h[0], h[1]); o.y = cvt_pk_bf16(h[2], h[3]); *(u32x2e*)(Hout + p) = o; }
;                 s += __shfl_xor(s, 16); s += __shfl_xor(s, 32);
;                 if (fq == 0) atomicAdd(rss_out + row, s); }
	v_fmamk_f32 v70, v143, 0x3a000000, v214
	v_mul_f32_e32 v71, 0x4b800000, v70
	v_cmp_gt_f32_e32 vcc, s65, v70
	s_waitcnt vmcnt(0) lgkmcnt(0)
	v_lshlrev_b32_e32 v154, 16, v148
	v_cndmask_b32_e32 v70, v70, v71, vcc
	v_rsq_f32_e32 v143, v70
	ds_read_b64 v[70:71], v132 offset:24832
	s_nop 0
	ds_read_b64 v[68:69], v131 offset:24832
	s_nop 0
	ds_read_b64 v[66:67], v133 offset:24832
	s_waitcnt vmcnt(0) lgkmcnt(0)
	v_mul_f32_e32 v140, 0x45800000, v143
	v_cndmask_b32_e32 v143, v143, v140, vcc
	v_mul_f32_e64 v62, v62, -v143
	v_mul_f32_e32 v62, 0x3fb8aa3b, v62
	v_exp_f32_e32 v62, v62
	v_mul_f32_e64 v63, v63, -v143
	v_mul_f32_e32 v63, 0x3fb8aa3b, v63
	v_exp_f32_e32 v63, v63
	v_add_f32_e32 v62, 1.0, v62
	v_rcp_f32_e32 v62, v62
	v_lshlrev_b64 v[140:141], 12, v[144:145]
	v_lshlrev_b32_e32 v144, 16, v146
	v_mul_f32_e64 v64, v64, -v143
	v_fmac_f32_e32 v144, v62, v154
	v_add_f32_e32 v62, 1.0, v63
	v_mul_f32_e32 v64, 0x3fb8aa3b, v64
	v_mul_f32_e64 v65, v65, -v143
	v_rcp_f32_e32 v62, v62
	v_exp_f32_e32 v64, v64
	v_mul_f32_e32 v65, 0x3fb8aa3b, v65
	v_exp_f32_e32 v65, v65
	v_and_b32_e32 v145, 0xffff0000, v146
	v_and_b32_e32 v63, 0xffff0000, v148
	v_fmac_f32_e32 v145, v62, v63
	v_add_f32_e32 v62, 1.0, v64
	v_mul_f32_e64 v58, v58, -v143
	v_rcp_f32_e32 v62, v62
	v_add_f32_e32 v63, 1.0, v65
	v_mul_f32_e32 v58, 0x3fb8aa3b, v58
	v_rcp_f32_e32 v63, v63
	v_exp_f32_e32 v58, v58
	v_lshlrev_b32_e32 v146, 16, v147
	v_lshlrev_b32_e32 v64, 16, v149
	v_and_b32_e32 v147, 0xffff0000, v147
	v_fmac_f32_e32 v146, v62, v64
	v_and_b32_e32 v62, 0xffff0000, v149
	v_mul_f32_e64 v59, v59, -v143
	v_fmac_f32_e32 v147, v63, v62
	v_add_f32_e32 v58, 1.0, v58
	v_mul_f32_e32 v59, 0x3fb8aa3b, v59
	v_mul_f32_e32 v62, v145, v145
	v_mul_f32_e32 v63, v147, v147
	v_rcp_f32_e32 v58, v58
	v_exp_f32_e32 v59, v59
	v_fmac_f32_e32 v62, v144, v144
	v_fmac_f32_e32 v63, v146, v146
	v_lshl_add_u64 v[64:65], s[48:49], 0, v[140:141]
	v_add_f32_e32 v148, v62, v63
	v_cvt_pk_bf16_f32 v62, v144, v145
	v_lshl_add_u64 v[64:65], v[136:137], 1, v[64:65]
	v_cvt_pk_bf16_f32 v63, v146, v147
	global_store_dwordx2 v[64:65], v[62:63], off
	s_waitcnt vmcnt(33)
	v_lshlrev_b32_e32 v62, 16, v150
	s_waitcnt vmcnt(32)
	v_lshlrev_b32_e32 v144, 16, v152
	v_mul_f32_e64 v60, v60, -v143
	v_fmac_f32_e32 v62, v58, v144
	v_add_f32_e32 v58, 1.0, v59
	v_mul_f32_e32 v60, 0x3fb8aa3b, v60
	v_mul_f32_e64 v54, v54, -v143
	v_rcp_f32_e32 v58, v58
	v_exp_f32_e32 v60, v60
	v_mul_f32_e32 v54, 0x3fb8aa3b, v54
	v_exp_f32_e32 v54, v54
	v_and_b32_e32 v63, 0xffff0000, v150
	v_and_b32_e32 v59, 0xffff0000, v152
	v_mul_f32_e64 v61, v61, -v143
	v_mul_f32_e32 v61, 0x3fb8aa3b, v61
	v_fmac_f32_e32 v63, v58, v59
	v_add_f32_e32 v58, 1.0, v60
	v_mul_f32_e64 v55, v55, -v143
	v_exp_f32_e32 v61, v61
	v_rcp_f32_e32 v58, v58
	v_add_f32_e32 v54, 1.0, v54
	v_mul_f32_e32 v55, 0x3fb8aa3b, v55
	v_rcp_f32_e32 v54, v54
	v_exp_f32_e32 v55, v55
	v_lshlrev_b32_e32 v140, 16, v151
	v_lshlrev_b32_e32 v60, 16, v153
	v_add_f32_e32 v59, 1.0, v61
	v_fmac_f32_e32 v140, v58, v60
	s_waitcnt vmcnt(31)
	v_lshlrev_b32_e32 v60, 16, v128
	v_and_b32_e32 v61, 0xffff0000, v128
	s_waitcnt vmcnt(30)
	v_lshlrev_b32_e32 v128, 16, v126
	v_mul_f32_e64 v56, v56, -v143
	v_fmac_f32_e32 v60, v54, v128
	v_add_f32_e32 v54, 1.0, v55
	v_mul_f32_e32 v56, 0x3fb8aa3b, v56
	v_mul_f32_e64 v57, v57, -v143
	v_rcp_f32_e32 v59, v59
	v_rcp_f32_e32 v54, v54
	v_exp_f32_e32 v56, v56
	v_mul_f32_e32 v57, 0x3fb8aa3b, v57
	v_exp_f32_e32 v57, v57
	v_and_b32_e32 v141, 0xffff0000, v151
	v_and_b32_e32 v58, 0xffff0000, v153
	v_and_b32_e32 v55, 0xffff0000, v126
	v_fmac_f32_e32 v141, v59, v58
	v_fmac_f32_e32 v61, v54, v55
	v_add_f32_e32 v54, 1.0, v56
	v_mul_f32_e64 v50, v50, -v143
	v_mul_f32_e32 v58, v63, v63
	v_mul_f32_e32 v59, v141, v141
	v_rcp_f32_e32 v54, v54
	v_add_f32_e32 v55, 1.0, v57
	v_mul_f32_e32 v50, 0x3fb8aa3b, v50
	v_fmac_f32_e32 v58, v62, v62
	v_fmac_f32_e32 v59, v140, v140
	v_rcp_f32_e32 v55, v55
	v_exp_f32_e32 v50, v50
	v_add_f32_e32 v58, v58, v59
	v_add_f32_e32 v59, v148, v58
	v_cvt_pk_bf16_f32 v58, v62, v63
	v_lshlrev_b32_e32 v62, 16, v129
	v_lshlrev_b32_e32 v56, 16, v127
	v_and_b32_e32 v63, 0xffff0000, v129
	v_fmac_f32_e32 v62, v54, v56
	v_and_b32_e32 v54, 0xffff0000, v127
	v_mul_f32_e64 v51, v51, -v143
	v_fmac_f32_e32 v63, v55, v54
	v_add_f32_e32 v50, 1.0, v50
	v_mul_f32_e32 v51, 0x3fb8aa3b, v51
	v_mul_f32_e32 v54, v61, v61
	v_mul_f32_e32 v55, v63, v63
	v_rcp_f32_e32 v50, v50
	v_exp_f32_e32 v51, v51
	v_fmac_f32_e32 v54, v60, v60
	v_fmac_f32_e32 v55, v62, v62
	v_add_f32_e32 v54, v54, v55
	v_add_f32_e32 v54, v54, v59
	s_waitcnt vmcnt(29)
	v_lshlrev_b32_e32 v55, 16, v124
	s_waitcnt vmcnt(28)
	v_lshlrev_b32_e32 v59, 16, v122
	v_mul_f32_e64 v52, v52, -v143
	v_fmac_f32_e32 v55, v50, v59
	v_add_f32_e32 v50, 1.0, v51
	v_mul_f32_e32 v52, 0x3fb8aa3b, v52
	v_mul_f32_e64 v53, v53, -v143
	v_rcp_f32_e32 v50, v50
	v_exp_f32_e32 v52, v52
	v_mul_f32_e32 v53, 0x3fb8aa3b, v53
	v_exp_f32_e32 v53, v53
	v_and_b32_e32 v56, 0xffff0000, v124
	v_and_b32_e32 v51, 0xffff0000, v122
	v_fmac_f32_e32 v56, v50, v51
	v_add_f32_e32 v50, 1.0, v52
	v_rcp_f32_e32 v50, v50
	v_add_f32_e32 v51, 1.0, v53
	v_rcp_f32_e32 v51, v51
	v_lshlrev_b32_e32 v57, 16, v125
	v_lshlrev_b32_e32 v52, 16, v123
	v_and_b32_e32 v124, 0xffff0000, v125
	v_fmac_f32_e32 v57, v50, v52
	v_and_b32_e32 v50, 0xffff0000, v123
	v_fmac_f32_e32 v124, v51, v50
	v_mul_f32_e32 v50, v56, v56
	v_mul_f32_e32 v51, v124, v124
	v_fmac_f32_e32 v50, v55, v55
	v_fmac_f32_e32 v51, v57, v57
	v_add_f32_e32 v50, v50, v51
	v_add_f32_e32 v50, v50, v54
	ds_bpermute_b32 v51, v206, v50
	v_cvt_pk_bf16_f32 v59, v140, v141
	global_store_dwordx2 v[64:65], v[58:59], off offset:32
	v_cvt_pk_bf16_f32 v52, v60, v61
	v_cvt_pk_bf16_f32 v53, v62, v63
	s_waitcnt lgkmcnt(0)
	v_add_f32_e32 v50, v50, v51
	ds_bpermute_b32 v51, v207, v50
	global_store_dwordx2 v[64:65], v[52:53], off offset:256
	v_cvt_pk_bf16_f32 v52, v55, v56
	v_cvt_pk_bf16_f32 v53, v57, v124
	global_store_dwordx2 v[64:65], v[52:53], off offset:288
	s_and_saveexec_b64 s[0:1], s[42:43]
	s_cbranch_execz .LBB0_55
	s_waitcnt lgkmcnt(0)
	v_add_f32_e32 v50, v50, v51
	global_atomic_add_f32 v[114:115], v50, off offset:512

; #define PG8_WAIT_V(n) asm volatile("s_waitcnt vmcnt(" #n ")" ::: "memory")
; #define PG8_BAR __builtin_amdgcn_s_barrier()
; template <class Epi, class Sched, bool ALIGN_EPI = false, bool SP2 = false>
; __device__ __forceinline__ void gemm_phase(PG8_LAS unsigned char* lds, const Gemm g, const Sched& S, const Epi& E, const int tid) {
;     ...
;     PG8_WAIT_V(0);
;     if constexpr (!ALIGN_EPI) { if (wr == 0) PG8_BAR; }
;     PG8_BAR;
.LBB0_61:
	s_waitcnt vmcnt(0)
	v_readlane_b32 s72, v254, 15
	s_cmpk_gt_u32 s13, 0xff
	v_readlane_b32 s71, v254, 14
	v_readlane_b32 s73, v254, 16
	v_mov_b32_e32 v222, v224
	v_mov_b32_e32 v225, 0x990
	v_mov_b32_e32 v226, 0xaa0
	v_mov_b32_e32 v227, 0xbb0
	s_cbranch_scc1 .LBB0_63
.LBB0_63:
	v_mov_b32_e32 v223, 0xffffc600
	v_mov_b32_e32 v224, 0xffff5200
	s_barrier

; #define PG8_STAGE(bufoff, gbase, voff) do { _Pragma("unroll") for (int _i = 0; _i < 2; ++_i) \
;         __builtin_amdgcn_global_load_lds((const unsigned*)((const char*)(gbase) + (voff)[_i]), (PG8_LAS unsigned*)(lds + (bufoff) + ldsw + _i * 8192), 16, 0, 0); } while (0)
; #define PG8_LDA(dst, b, h) do { _Pragma("unroll") for (int m = 0; m < 4; ++m) _Pragma("unroll") for (int k = 0; k < 2; ++k) dst[m][k] = *(const PG8_LAS bf16x8*)(lds + PG8_SA(b, h) + aoff + m * 2048 + k * 1024); } while (0)
; #define PG8_LDB(dst, b, h) do { _Pragma("unroll") for (int n = 0; n < 2; ++n) _Pragma("unroll") for (int k = 0; k < 2; ++k) dst[n][k] = *(const PG8_LAS bf16x8*)(lds + PG8_SB(b, h) + boff + n * 2048 + k * 1024); } while (0)
; #define PG8_MMA(ai, bj, At, Bt) do { __builtin_amdgcn_s_setprio(1); _Pragma("unroll") for (int m = 0; m < 4; ++m) _Pragma("unroll") for (int n = 0; n < 2; ++n) _Pragma("unroll") for (int k = 0; k < 2; ++k) \
;         acc[ai][bj][m][n] = __builtin_amdgcn_mfma_f32_16x16x32_bf16(Bt[n][k], At[m][k], acc[ai][bj][m][n], 0, 0, 0); __builtin_amdgcn_s_setprio(0); } while (0)
; #define PG8_WAIT_V(n) asm volatile("s_waitcnt vmcnt(" #n ")" ::: "memory")
; #define PG8_WAIT_L(n) asm volatile("s_waitcnt lgkmcnt(" #n ")" ::: "memory")
; #define PG8_BAR __builtin_amdgcn_s_barrier()
; #define PG8_SCHED __builtin_amdgcn_sched_barrier(0)
; template <class Epi, class Sched, bool ALIGN_EPI = false, bool SP2 = false>
; __device__ __forceinline__ void gemm_phase(PG8_LAS unsigned char* lds, const Gemm g, const Sched& S, const Epi& E, const int tid) {
;     ...
;             PG8_LDB(B0, 0, 0); PG8_LDB(B1, 0, 1); PG8_SCHED; PG8_LDA(At, 0, 0); PG8_STAGE(PG8_SA(1, 1), a1 + hstep, voffA);
;             PG8_WAIT_V(8); PG8_WAIT_L(0); PG8_BAR; PG8_MMA(0, 0, At, B0); PG8_MMA(0, 1, At, B1); PG8_BAR; PG8_SCHED;
;             PG8_LDA(At, 0, 1); PG8_STAGE(PG8_SB(0, 0), b2, voffB); PG8_STAGE(PG8_SB(0, 1), b2 + hstep, voffB); PG8_STAGE(PG8_SA(0, 0), a2, voffA);
;             PG8_WAIT_V(8); PG8_WAIT_L(0); PG8_BAR; PG8_MMA(1, 0, At, B0); PG8_MMA(1, 1, At, B1); PG8_BAR; PG8_SCHED;
.LBB0_92:
	s_add_u32 s0, s8, 0xfff80080
	s_addc_u32 s1, s9, -1
	s_add_i32 s35, 0, 0x10000
	s_cmp_eq_u32 s34, 28
	s_cselect_b32 s3, s10, s1
	s_cselect_b32 s2, s11, s0
	s_cselect_b32 s1, s28, s31
	s_cselect_b32 s0, s29, s30
	s_add_i32 s38, 0, 0x14000
	v_add_u32_e32 v148, s35, v175
	v_add_u32_e32 v164, s38, v175
	ds_read_b128 v[136:139], v148
	ds_read_b128 v[140:143], v148 offset:1024
	ds_read_b128 v[144:147], v148 offset:2048
	ds_read_b128 v[148:151], v148 offset:3072
	ds_read_b128 v[152:155], v164
	ds_read_b128 v[156:159], v164 offset:1024
	ds_read_b128 v[160:163], v164 offset:2048
	ds_read_b128 v[164:167], v164 offset:3072
	v_lshl_add_u64 v[172:173], s[8:9], 0, v[132:133]
	s_add_i32 m0, s5, 0xc000
	ds_read_b128 v[168:171], v177
	ds_read_b128 v[178:181], v177 offset:1024
	ds_read_b128 v[192:195], v177 offset:2048
	ds_read_b128 v[196:199], v177 offset:3072
	ds_read_b128 v[200:203], v177 offset:4096
	ds_read_b128 v[204:207], v177 offset:5120
	ds_read_b128 v[208:211], v177 offset:6144
	ds_read_b128 v[236:239], v177 offset:7168
	global_load_lds_dwordx4 v[172:173], off
	v_lshl_add_u64 v[172:173], s[8:9], 0, v[134:135]
	s_add_i32 m0, s5, 0xe000
	s_nop 0
	global_load_lds_dwordx4 v[172:173], off
	s_waitcnt vmcnt(8)
	s_waitcnt lgkmcnt(0)
	s_barrier
	s_setprio 1
	s_waitcnt lgkmcnt(0)
	v_mfma_f32_16x16x32_bf16 v[126:129], v[136:139], v[168:171], v[126:129]
	v_mfma_f32_16x16x32_bf16 v[122:125], v[144:147], v[168:171], v[122:125]
	v_mfma_f32_16x16x32_bf16 v[110:113], v[136:139], v[192:195], v[110:113]
	v_mfma_f32_16x16x32_bf16 v[106:109], v[144:147], v[192:195], v[106:109]
	v_mfma_f32_16x16x32_bf16 v[94:97], v[136:139], v[200:203], v[94:97]
	v_mfma_f32_16x16x32_bf16 v[90:93], v[144:147], v[200:203], v[90:93]
	v_mfma_f32_16x16x32_bf16 v[78:81], v[136:139], v[208:211], v[78:81]
	v_mfma_f32_16x16x32_bf16 v[74:77], v[144:147], v[208:211], v[74:77]
	v_mfma_f32_16x16x32_bf16 v[126:129], v[140:143], v[178:181], v[126:129]
	v_mfma_f32_16x16x32_bf16 v[122:125], v[148:151], v[178:181], v[122:125]
	v_mfma_f32_16x16x32_bf16 v[110:113], v[140:143], v[196:199], v[110:113]
	v_mfma_f32_16x16x32_bf16 v[106:109], v[148:151], v[196:199], v[106:109]
	v_mfma_f32_16x16x32_bf16 v[94:97], v[140:143], v[204:207], v[94:97]
	v_mfma_f32_16x16x32_bf16 v[90:93], v[148:151], v[204:207], v[90:93]
	v_mfma_f32_16x16x32_bf16 v[78:81], v[140:143], v[236:239], v[78:81]
	v_mfma_f32_16x16x32_bf16 v[74:77], v[148:151], v[236:239], v[74:77]
	s_setprio 0
	s_setprio 1
	v_mfma_f32_16x16x32_bf16 v[118:121], v[152:155], v[168:171], v[118:121]
	v_mfma_f32_16x16x32_bf16 v[114:117], v[160:163], v[168:171], v[114:117]
	v_mfma_f32_16x16x32_bf16 v[102:105], v[152:155], v[192:195], v[102:105]
	v_mfma_f32_16x16x32_bf16 v[98:101], v[160:163], v[192:195], v[98:101]
	v_mfma_f32_16x16x32_bf16 v[86:89], v[152:155], v[200:203], v[86:89]
	v_mfma_f32_16x16x32_bf16 v[82:85], v[160:163], v[200:203], v[82:85]
	v_mfma_f32_16x16x32_bf16 v[70:73], v[152:155], v[208:211], v[70:73]
	v_mfma_f32_16x16x32_bf16 v[66:69], v[160:163], v[208:211], v[66:69]
	v_mfma_f32_16x16x32_bf16 v[118:121], v[156:159], v[178:181], v[118:121]
	v_mfma_f32_16x16x32_bf16 v[114:117], v[164:167], v[178:181], v[114:117]
	v_mfma_f32_16x16x32_bf16 v[102:105], v[156:159], v[196:199], v[102:105]
	v_mfma_f32_16x16x32_bf16 v[98:101], v[164:167], v[196:199], v[98:101]
	v_mfma_f32_16x16x32_bf16 v[86:89], v[156:159], v[204:207], v[86:89]
	v_mfma_f32_16x16x32_bf16 v[82:85], v[164:167], v[204:207], v[82:85]
	v_mfma_f32_16x16x32_bf16 v[70:73], v[156:159], v[236:239], v[70:73]
	v_mfma_f32_16x16x32_bf16 v[66:69], v[164:167], v[236:239], v[66:69]
	s_setprio 0
	s_barrier
	s_add_i32 s35, s35, s19
	v_lshl_add_u64 v[172:173], s[0:1], 0, v[0:1]
	s_mov_b32 m0, s35
	ds_read_b128 v[168:171], v177 offset:16384
	ds_read_b128 v[178:181], v177 offset:17408
	ds_read_b128 v[192:195], v177 offset:18432
	ds_read_b128 v[196:199], v177 offset:19456
	ds_read_b128 v[200:203], v177 offset:20480
	ds_read_b128 v[204:207], v177 offset:21504
	ds_read_b128 v[208:211], v177 offset:22528
	ds_read_b128 v[236:239], v177 offset:23552
	global_load_lds_dwordx4 v[172:173], off
	s_add_i32 m0, s35, 0x2000
	s_add_u32 s36, s0, 0x80000
	v_lshl_add_u64 v[212:213], s[0:1], 0, v[130:131]
	s_addc_u32 s37, s1, 0
	s_add_i32 s35, s38, s19
	global_load_lds_dwordx4 v[212:213], off
	v_lshl_add_u64 v[240:241], s[36:37], 0, v[0:1]
	s_mov_b32 m0, s35
	v_lshl_add_u64 v[242:243], s[2:3], 0, v[130:131]
	global_load_lds_dwordx4 v[240:241], off
	v_lshl_add_u64 v[240:241], s[36:37], 0, v[130:131]
	s_add_i32 m0, s35, 0x2000
	s_nop 0
	global_load_lds_dwordx4 v[240:241], off
	v_lshl_add_u64 v[240:241], s[2:3], 0, v[0:1]
	s_mov_b32 m0, s5
	s_nop 0
	global_load_lds_dwordx4 v[240:241], off
	s_mov_b32 m0, s7
	s_nop 0
	global_load_lds_dwordx4 v[242:243], off
	s_waitcnt vmcnt(8)
	s_waitcnt lgkmcnt(0)
	s_barrier
; #define PG8_STAGE(bufoff, gbase, voff) do { _Pragma("unroll") for (int _i = 0; _i < 2; ++_i) \
;         __builtin_amdgcn_global_load_lds((const unsigned*)((const char*)(gbase) + (voff)[_i]), (PG8_LAS unsigned*)(lds + (bufoff) + ldsw + _i * 8192), 16, 0, 0); } while (0)
; #define PG8_LDA(dst, b, h) do { _Pragma("unroll") for (int m = 0; m < 4; ++m) _Pragma("unroll") for (int k = 0; k < 2; ++k) dst[m][k] = *(const PG8_LAS bf16x8*)(lds + PG8_SA(b, h) + aoff + m * 2048 + k * 1024); } while (0)
; #define PG8_LDB(dst, b, h) do { _Pragma("unroll") for (int n = 0; n < 2; ++n) _Pragma("unroll") for (int k = 0; k < 2; ++k) dst[n][k] = *(const PG8_LAS bf16x8*)(lds + PG8_SB(b, h) + boff + n * 2048 + k * 1024); } while (0)
; #define PG8_MMA(ai, bj, At, Bt) do { __builtin_amdgcn_s_setprio(1); _Pragma("unroll") for (int m = 0; m < 4; ++m) _Pragma("unroll") for (int n = 0; n < 2; ++n) _Pragma("unroll") for (int k = 0; k < 2; ++k) \
;         acc[ai][bj][m][n] = __builtin_amdgcn_mfma_f32_16x16x32_bf16(Bt[n][k], At[m][k], acc[ai][bj][m][n], 0, 0, 0); __builtin_amdgcn_s_setprio(0); } while (0)
; #define PG8_WAIT_V(n) asm volatile("s_waitcnt vmcnt(" #n ")" ::: "memory")
; #define PG8_WAIT_L(n) asm volatile("s_waitcnt lgkmcnt(" #n ")" ::: "memory")
; #define PG8_BAR __builtin_amdgcn_s_barrier()
; #define PG8_SCHED __builtin_amdgcn_sched_barrier(0)
; template <class Epi, class Sched, bool ALIGN_EPI = false, bool SP2 = false>
; __device__ __forceinline__ void gemm_phase(PG8_LAS unsigned char* lds, const Gemm g, const Sched& S, const Epi& E, const int tid) {
;     ...
;             PG8_WAIT_V(8); PG8_WAIT_L(0); PG8_BAR; PG8_MMA(1, 0, At, B0); PG8_MMA(1, 1, At, B1); PG8_BAR; PG8_SCHED;
;             PG8_LDB(B0, 1, 0); PG8_LDB(B1, 1, 1); PG8_SCHED; PG8_LDA(At, 1, 0); PG8_STAGE(PG8_SA(0, 1), a2 + hstep, voffA);
;             PG8_WAIT_V(8); PG8_WAIT_L(0); PG8_BAR; PG8_MMA(0, 0, At, B0); PG8_MMA(0, 1, At, B1); PG8_BAR; PG8_SCHED;
	s_setprio 1
	s_waitcnt lgkmcnt(0)
	v_mfma_f32_16x16x32_bf16 v[62:65], v[136:139], v[168:171], v[62:65]
	v_mfma_f32_16x16x32_bf16 v[58:61], v[144:147], v[168:171], v[58:61]
	v_mfma_f32_16x16x32_bf16 v[46:49], v[136:139], v[192:195], v[46:49]
	v_mfma_f32_16x16x32_bf16 v[42:45], v[144:147], v[192:195], v[42:45]
	v_mfma_f32_16x16x32_bf16 v[30:33], v[136:139], v[200:203], v[30:33]
	v_mfma_f32_16x16x32_bf16 v[26:29], v[144:147], v[200:203], v[26:29]
	v_mfma_f32_16x16x32_bf16 v[14:17], v[136:139], v[208:211], v[14:17]
	v_mfma_f32_16x16x32_bf16 v[10:13], v[144:147], v[208:211], v[10:13]
	v_mfma_f32_16x16x32_bf16 v[62:65], v[140:143], v[178:181], v[62:65]
	v_mfma_f32_16x16x32_bf16 v[58:61], v[148:151], v[178:181], v[58:61]
	v_mfma_f32_16x16x32_bf16 v[46:49], v[140:143], v[196:199], v[46:49]
	v_mfma_f32_16x16x32_bf16 v[42:45], v[148:151], v[196:199], v[42:45]
	v_mfma_f32_16x16x32_bf16 v[30:33], v[140:143], v[204:207], v[30:33]
	v_mfma_f32_16x16x32_bf16 v[26:29], v[148:151], v[204:207], v[26:29]
	v_mfma_f32_16x16x32_bf16 v[14:17], v[140:143], v[236:239], v[14:17]
	v_mfma_f32_16x16x32_bf16 v[10:13], v[148:151], v[236:239], v[10:13]
	s_setprio 0
	s_setprio 1
	v_mfma_f32_16x16x32_bf16 v[54:57], v[152:155], v[168:171], v[54:57]
	v_mfma_f32_16x16x32_bf16 v[50:53], v[160:163], v[168:171], v[50:53]
	v_mfma_f32_16x16x32_bf16 v[38:41], v[152:155], v[192:195], v[38:41]
	v_mfma_f32_16x16x32_bf16 v[34:37], v[160:163], v[192:195], v[34:37]
	v_mfma_f32_16x16x32_bf16 v[22:25], v[152:155], v[200:203], v[22:25]
	v_mfma_f32_16x16x32_bf16 v[18:21], v[160:163], v[200:203], v[18:21]
	v_mfma_f32_16x16x32_bf16 v[6:9], v[152:155], v[208:211], v[6:9]
	v_mfma_f32_16x16x32_bf16 v[2:5], v[160:163], v[208:211], v[2:5]
	v_mfma_f32_16x16x32_bf16 v[54:57], v[156:159], v[178:181], v[54:57]
	v_mfma_f32_16x16x32_bf16 v[50:53], v[164:167], v[178:181], v[50:53]
	v_mfma_f32_16x16x32_bf16 v[38:41], v[156:159], v[196:199], v[38:41]
	v_mfma_f32_16x16x32_bf16 v[34:37], v[164:167], v[196:199], v[34:37]
	v_mfma_f32_16x16x32_bf16 v[22:25], v[156:159], v[204:207], v[22:25]
	v_mfma_f32_16x16x32_bf16 v[18:21], v[164:167], v[204:207], v[18:21]
	v_mfma_f32_16x16x32_bf16 v[6:9], v[156:159], v[236:239], v[6:9]
	v_mfma_f32_16x16x32_bf16 v[2:5], v[164:167], v[236:239], v[2:5]
	s_setprio 0
	s_barrier
	s_add_i32 s35, 0, 0x18000
	s_add_i32 s36, 0, 0x1c000
	v_add_u32_e32 v148, s35, v175
	v_add_u32_e32 v164, s36, v175
	ds_read_b128 v[136:139], v148
	ds_read_b128 v[140:143], v148 offset:1024
	ds_read_b128 v[144:147], v148 offset:2048
	ds_read_b128 v[148:151], v148 offset:3072
	ds_read_b128 v[152:155], v164
	ds_read_b128 v[156:159], v164 offset:1024
	ds_read_b128 v[160:163], v164 offset:2048
	ds_read_b128 v[164:167], v164 offset:3072
	s_add_u32 s2, s2, 0x80000
	s_addc_u32 s3, s3, 0
	s_mov_b32 m0, s20
	v_lshl_add_u64 v[244:245], s[2:3], 0, v[0:1]
	ds_read_b128 v[168:171], v177 offset:32768
	ds_read_b128 v[178:181], v177 offset:33792
	ds_read_b128 v[192:195], v177 offset:34816
	ds_read_b128 v[196:199], v177 offset:35840
	ds_read_b128 v[200:203], v177 offset:36864
	ds_read_b128 v[204:207], v177 offset:37888
	ds_read_b128 v[208:211], v177 offset:38912
	ds_read_b128 v[236:239], v177 offset:39936
	global_load_lds_dwordx4 v[244:245], off
	v_lshl_add_u64 v[244:245], s[2:3], 0, v[130:131]
	s_mov_b32 m0, s21
	s_nop 0
	global_load_lds_dwordx4 v[244:245], off
	s_waitcnt vmcnt(8)
	s_waitcnt lgkmcnt(0)
	s_barrier
	s_setprio 1
	s_waitcnt lgkmcnt(0)
	v_mfma_f32_16x16x32_bf16 v[126:129], v[136:139], v[168:171], v[126:129]
	v_mfma_f32_16x16x32_bf16 v[122:125], v[144:147], v[168:171], v[122:125]
	v_mfma_f32_16x16x32_bf16 v[110:113], v[136:139], v[192:195], v[110:113]
	v_mfma_f32_16x16x32_bf16 v[106:109], v[144:147], v[192:195], v[106:109]
	v_mfma_f32_16x16x32_bf16 v[94:97], v[136:139], v[200:203], v[94:97]
	v_mfma_f32_16x16x32_bf16 v[90:93], v[144:147], v[200:203], v[90:93]
	v_mfma_f32_16x16x32_bf16 v[78:81], v[136:139], v[208:211], v[78:81]
	v_mfma_f32_16x16x32_bf16 v[74:77], v[144:147], v[208:211], v[74:77]
	v_mfma_f32_16x16x32_bf16 v[126:129], v[140:143], v[178:181], v[126:129]
	v_mfma_f32_16x16x32_bf16 v[122:125], v[148:151], v[178:181], v[122:125]
	v_mfma_f32_16x16x32_bf16 v[110:113], v[140:143], v[196:199], v[110:113]
	v_mfma_f32_16x16x32_bf16 v[106:109], v[148:151], v[196:199], v[106:109]
	v_mfma_f32_16x16x32_bf16 v[94:97], v[140:143], v[204:207], v[94:97]
	v_mfma_f32_16x16x32_bf16 v[90:93], v[148:151], v[204:207], v[90:93]
	v_mfma_f32_16x16x32_bf16 v[78:81], v[140:143], v[236:239], v[78:81]
	v_mfma_f32_16x16x32_bf16 v[74:77], v[148:151], v[236:239], v[74:77]
	s_setprio 0
	s_setprio 1
	v_mfma_f32_16x16x32_bf16 v[118:121], v[152:155], v[168:171], v[118:121]
	v_mfma_f32_16x16x32_bf16 v[114:117], v[160:163], v[168:171], v[114:117]
	v_mfma_f32_16x16x32_bf16 v[102:105], v[152:155], v[192:195], v[102:105]
	v_mfma_f32_16x16x32_bf16 v[98:101], v[160:163], v[192:195], v[98:101]
	v_mfma_f32_16x16x32_bf16 v[86:89], v[152:155], v[200:203], v[86:89]
	v_mfma_f32_16x16x32_bf16 v[82:85], v[160:163], v[200:203], v[82:85]
	v_mfma_f32_16x16x32_bf16 v[70:73], v[152:155], v[208:211], v[70:73]
	v_mfma_f32_16x16x32_bf16 v[66:69], v[160:163], v[208:211], v[66:69]
	v_mfma_f32_16x16x32_bf16 v[118:121], v[156:159], v[178:181], v[118:121]
	v_mfma_f32_16x16x32_bf16 v[114:117], v[164:167], v[178:181], v[114:117]
	v_mfma_f32_16x16x32_bf16 v[102:105], v[156:159], v[196:199], v[102:105]
	v_mfma_f32_16x16x32_bf16 v[98:101], v[164:167], v[196:199], v[98:101]
	v_mfma_f32_16x16x32_bf16 v[86:89], v[156:159], v[204:207], v[86:89]
	v_mfma_f32_16x16x32_bf16 v[82:85], v[164:167], v[204:207], v[82:85]
	v_mfma_f32_16x16x32_bf16 v[70:73], v[156:159], v[236:239], v[70:73]
	v_mfma_f32_16x16x32_bf16 v[66:69], v[164:167], v[236:239], v[66:69]
	s_setprio 0
	s_barrier
; #define PG8_STAGE(bufoff, gbase, voff) do { _Pragma("unroll") for (int _i = 0; _i < 2; ++_i) \
;         __builtin_amdgcn_global_load_lds((const unsigned*)((const char*)(gbase) + (voff)[_i]), (PG8_LAS unsigned*)(lds + (bufoff) + ldsw + _i * 8192), 16, 0, 0); } while (0)
; #define PG8_LDA(dst, b, h) do { _Pragma("unroll") for (int m = 0; m < 4; ++m) _Pragma("unroll") for (int k = 0; k < 2; ++k) dst[m][k] = *(const PG8_LAS bf16x8*)(lds + PG8_SA(b, h) + aoff + m * 2048 + k * 1024); } while (0)
; #define PG8_MMA(ai, bj, At, Bt) do { __builtin_amdgcn_s_setprio(1); _Pragma("unroll") for (int m = 0; m < 4; ++m) _Pragma("unroll") for (int n = 0; n < 2; ++n) _Pragma("unroll") for (int k = 0; k < 2; ++k) \
;         acc[ai][bj][m][n] = __builtin_amdgcn_mfma_f32_16x16x32_bf16(Bt[n][k], At[m][k], acc[ai][bj][m][n], 0, 0, 0); __builtin_amdgcn_s_setprio(0); } while (0)
; #define PG8_WAIT_V(n) asm volatile("s_waitcnt vmcnt(" #n ")" ::: "memory")
; #define PG8_WAIT_L(n) asm volatile("s_waitcnt lgkmcnt(" #n ")" ::: "memory")
; #define PG8_BAR __builtin_amdgcn_s_barrier()
; #define PG8_SCHED __builtin_amdgcn_sched_barrier(0)
; template <class Epi, class Sched, bool ALIGN_EPI = false, bool SP2 = false>
; __device__ __forceinline__ void gemm_phase(PG8_LAS unsigned char* lds, const Gemm g, const Sched& S, const Epi& E, const int tid) {
;     ...
;             PG8_LDA(At, 1, 1); PG8_STAGE(PG8_SB(1, 0), b3, voffB); PG8_STAGE(PG8_SB(1, 1), b3 + hstep, voffB); PG8_STAGE(PG8_SA(1, 0), a3, voffA);
;             PG8_WAIT_V(8); PG8_WAIT_L(0); PG8_BAR; PG8_MMA(1, 0, At, B0); PG8_MMA(1, 1, At, B1); PG8_BAR; PG8_SCHED;
;     ...
;         if constexpr (ALIGN_EPI) { if (wr == 0) PG8_BAR; }
	s_add_i32 s2, s35, s19
	v_lshl_add_u64 v[172:173], v[172:173], 0, s[24:25]
	s_mov_b32 m0, s2
	ds_read_b128 v[168:171], v177 offset:49152
	ds_read_b128 v[178:181], v177 offset:50176
	ds_read_b128 v[192:195], v177 offset:51200
	ds_read_b128 v[196:199], v177 offset:52224
	ds_read_b128 v[200:203], v177 offset:53248
	ds_read_b128 v[204:207], v177 offset:54272
	ds_read_b128 v[208:211], v177 offset:55296
	ds_read_b128 v[236:239], v177 offset:56320
	global_load_lds_dwordx4 v[172:173], off
	s_add_i32 m0, s2, 0x2000
	s_add_u32 s0, s0, 0x80080
	v_lshl_add_u64 v[172:173], v[212:213], 0, s[24:25]
	s_addc_u32 s1, s1, 0
	s_add_i32 s2, s36, s19
	global_load_lds_dwordx4 v[172:173], off
	v_lshl_add_u64 v[172:173], s[0:1], 0, v[0:1]
	s_mov_b32 m0, s2
	s_nop 0
	global_load_lds_dwordx4 v[172:173], off
	v_lshl_add_u64 v[172:173], s[0:1], 0, v[130:131]
	s_add_i32 m0, s2, 0x2000
	s_nop 0
	global_load_lds_dwordx4 v[172:173], off
	v_lshl_add_u64 v[172:173], v[240:241], 0, s[24:25]
	s_mov_b32 m0, s22
	s_nop 0
	global_load_lds_dwordx4 v[172:173], off
	v_lshl_add_u64 v[172:173], v[242:243], 0, s[24:25]
	s_mov_b32 m0, s23
	s_nop 0
	global_load_lds_dwordx4 v[172:173], off
	s_waitcnt vmcnt(8)
	s_waitcnt lgkmcnt(0)
	s_barrier
	s_setprio 1
	s_waitcnt lgkmcnt(0)
	v_mfma_f32_16x16x32_bf16 v[62:65], v[136:139], v[168:171], v[62:65]
	v_mfma_f32_16x16x32_bf16 v[58:61], v[144:147], v[168:171], v[58:61]
	v_mfma_f32_16x16x32_bf16 v[46:49], v[136:139], v[192:195], v[46:49]
	v_mfma_f32_16x16x32_bf16 v[42:45], v[144:147], v[192:195], v[42:45]
	v_mfma_f32_16x16x32_bf16 v[30:33], v[136:139], v[200:203], v[30:33]
	v_mfma_f32_16x16x32_bf16 v[26:29], v[144:147], v[200:203], v[26:29]
	v_mfma_f32_16x16x32_bf16 v[14:17], v[136:139], v[208:211], v[14:17]
	v_mfma_f32_16x16x32_bf16 v[10:13], v[144:147], v[208:211], v[10:13]
	v_mfma_f32_16x16x32_bf16 v[62:65], v[140:143], v[178:181], v[62:65]
	v_mfma_f32_16x16x32_bf16 v[58:61], v[148:151], v[178:181], v[58:61]
	v_mfma_f32_16x16x32_bf16 v[46:49], v[140:143], v[196:199], v[46:49]
	v_mfma_f32_16x16x32_bf16 v[42:45], v[148:151], v[196:199], v[42:45]
	v_mfma_f32_16x16x32_bf16 v[30:33], v[140:143], v[204:207], v[30:33]
	v_mfma_f32_16x16x32_bf16 v[26:29], v[148:151], v[204:207], v[26:29]
	v_mfma_f32_16x16x32_bf16 v[14:17], v[140:143], v[236:239], v[14:17]
	v_mfma_f32_16x16x32_bf16 v[10:13], v[148:151], v[236:239], v[10:13]
	s_setprio 0
	s_setprio 1
	v_mfma_f32_16x16x32_bf16 v[54:57], v[152:155], v[168:171], v[54:57]
	v_mfma_f32_16x16x32_bf16 v[50:53], v[160:163], v[168:171], v[50:53]
	v_mfma_f32_16x16x32_bf16 v[38:41], v[152:155], v[192:195], v[38:41]
	v_mfma_f32_16x16x32_bf16 v[34:37], v[160:163], v[192:195], v[34:37]
	v_mfma_f32_16x16x32_bf16 v[22:25], v[152:155], v[200:203], v[22:25]
	v_mfma_f32_16x16x32_bf16 v[18:21], v[160:163], v[200:203], v[18:21]
	v_mfma_f32_16x16x32_bf16 v[6:9], v[152:155], v[208:211], v[6:9]
	v_mfma_f32_16x16x32_bf16 v[2:5], v[160:163], v[208:211], v[2:5]
	v_mfma_f32_16x16x32_bf16 v[54:57], v[156:159], v[178:181], v[54:57]
	v_mfma_f32_16x16x32_bf16 v[50:53], v[164:167], v[178:181], v[50:53]
	v_mfma_f32_16x16x32_bf16 v[38:41], v[156:159], v[196:199], v[38:41]
	v_mfma_f32_16x16x32_bf16 v[34:37], v[164:167], v[196:199], v[34:37]
	v_mfma_f32_16x16x32_bf16 v[22:25], v[156:159], v[204:207], v[22:25]
	v_mfma_f32_16x16x32_bf16 v[18:21], v[164:167], v[204:207], v[18:21]
	v_mfma_f32_16x16x32_bf16 v[6:9], v[156:159], v[236:239], v[6:9]
	v_mfma_f32_16x16x32_bf16 v[2:5], v[164:167], v[236:239], v[2:5]
	s_setprio 0
	s_barrier
	s_add_i32 s34, s34, 2
	s_add_u32 s8, s8, 0x100
	s_addc_u32 s9, s9, 0
	s_add_u32 s30, s30, 0x100
	s_addc_u32 s31, s31, 0
	s_cmp_gt_u32 s34, 29
	s_cbranch_scc0 .LBB0_92
	s_cmpk_gt_u32 s13, 0xff
	s_cbranch_scc1 .Lepi2_noalign
	s_barrier
;     __device__ __forceinline__ void operator()(const f32x4 (&acc)[2][2][4][2], const Unit& u, int wr, int wc, int fr, int fq) const {
;         const int row0 = u.pm * BM + wr * 64 + fr, col0 = u.pn * BM + wc * 32 + 4 * fq;
; #pragma unroll
;         for (int ai = 0; ai < 2; ++ai) {
;             u32x2e hw[4][2][2], pw[4][2][2]; float scv[4];
; #pragma unroll
;             for (int m = 0; m < 4; ++m) { const int row = row0 + ai * HALF + m * 16; const size_t ro = (size_t)row * 2048 + col0;
;                 scv[m] = GATE ? rss_in[row] : 0.f;
; #pragma unroll
;                 for (int bj = 0; bj < 2; ++bj)
; #pragma unroll
;                     for (int n = 0; n < 2; ++n) { const size_t p = ro + bj * HALF + n * 16; hw[m][bj][n] = *(const u32x2e*)(Hin + p); if (GATE) pw[m][bj][n] = *(const u32x2e*)(PP + p); else pw[m][bj][n] = (u32x2e){0u, 0u}; } }
; #pragma unroll
;             for (int m = 0; m < 4; ++m) { const int row = row0 + ai * HALF + m * 16; const size_t ro = (size_t)row * 2048 + col0;
;                 float sc = 1.f; if (GATE) sc = rsqrtf(scv[m] * (1.f / 2048.f) + 1e-6f);
;                 float s = 0.f;
; #pragma unroll
;                 for (int bj = 0; bj < 2; ++bj)
; #pragma unroll
;                     for (int n = 0; n < 2; ++n) { const size_t p = ro + bj * HALF + n * 16; const u32x2e hh = hw[m][bj][n], pp = pw[m][bj][n]; const f32x4 a = acc[ai][bj][m][n];
;                         f32x4 h; h[0] = __uint_as_float(hh.x << 16); h[1] = __uint_as_float(hh.x & 0xffff0000u); h[2] = __uint_as_float(hh.y << 16); h[3] = __uint_as_float(hh.y & 0xffff0000u);
;                         if (GATE) {
;                             h[0] += __builtin_amdgcn_rcpf(1.f + __expf(-sc * a[0])) * __uint_as_float(pp.x << 16); h[1] += __builtin_amdgcn_rcpf(1.f + __expf(-sc * a[1])) * __uint_as_float(pp.x & 0xffff0000u);
;                             h[2] += __builtin_amdgcn_rcpf(1.f + __expf(-sc * a[2])) * __uint_as_float(pp.y << 16); h[3] += __builtin_amdgcn_rcpf(1.f + __expf(-sc * a[3])) * __uint_as_float(pp.y & 0xffff0000u); }
;                         else h = h + a;
;                         s += (h[0] * h[0] + h[1] * h[1]) + (h[2] * h[2] + h[3] * h[3]);
;                         u32x2e o; o.x = cvt_pk_bf16(h[0], h[1]); o.y = cvt_pk_bf16(h[2], h[3]); *(u32x2e*)(Hout + p) = o; }
;                 s += __shfl_xor(s, 16); s += __shfl_xor(s, 32);
.Lepi2_noalign:
	v_lshl_or_b32 v136, s6, 8, v176
	v_lshl_add_u32 v170, s4, 8, v174
	v_ashrrev_i32_e32 v137, 31, v136
	v_lshlrev_b64 v[178:179], 1, v[136:137]
	v_ashrrev_i32_e32 v171, 31, v170
	v_lshl_add_u64 v[138:139], s[46:47], 0, v[178:179]
	v_lshlrev_b64 v[140:141], 12, v[170:171]
	v_lshl_add_u64 v[142:143], v[138:139], 0, v[140:141]
	global_load_dwordx2 v[180:181], v[142:143], off
	global_load_dwordx2 v[192:193], v[142:143], off offset:32
	global_load_dwordx2 v[194:195], v[142:143], off offset:256
	global_load_dwordx2 v[196:197], v[142:143], off offset:288
	v_or_b32_e32 v142, 16, v170
	v_ashrrev_i32_e32 v143, 31, v142
	v_lshlrev_b64 v[168:169], 12, v[142:143]
	v_lshl_add_u64 v[142:143], v[138:139], 0, v[168:169]
	global_load_dwordx2 v[172:173], v[142:143], off
	global_load_dwordx2 v[166:167], v[142:143], off offset:32
	global_load_dwordx2 v[164:165], v[142:143], off offset:256
	global_load_dwordx2 v[162:163], v[142:143], off offset:288
	v_or_b32_e32 v142, 32, v170
	v_ashrrev_i32_e32 v143, 31, v142
	v_lshlrev_b64 v[158:159], 12, v[142:143]
	v_lshl_add_u64 v[142:143], v[138:139], 0, v[158:159]
	global_load_dwordx2 v[160:161], v[142:143], off
	global_load_dwordx2 v[156:157], v[142:143], off offset:32
	global_load_dwordx2 v[152:153], v[142:143], off offset:256
	global_load_dwordx2 v[148:149], v[142:143], off offset:288
	v_or_b32_e32 v142, 48, v170
	v_ashrrev_i32_e32 v143, 31, v142
	v_lshlrev_b64 v[144:145], 12, v[142:143]
	v_lshl_add_u64 v[142:143], v[138:139], 0, v[144:145]
	global_load_dwordx2 v[154:155], v[142:143], off
	global_load_dwordx2 v[150:151], v[142:143], off offset:32
	global_load_dwordx2 v[146:147], v[142:143], off offset:256
	s_nop 0
	global_load_dwordx2 v[142:143], v[142:143], off offset:288
	s_waitcnt vmcnt(0)
	v_lshlrev_b32_e32 v198, 16, v180
	v_and_b32_e32 v199, 0xffff0000, v180
	v_lshlrev_b32_e32 v180, 16, v181
	v_and_b32_e32 v181, 0xffff0000, v181
	v_pk_add_f32 v[128:129], v[128:129], v[180:181]
	v_pk_add_f32 v[126:127], v[126:127], v[198:199]
	v_mul_f32_e32 v181, v129, v129
	v_mul_f32_e32 v180, v127, v127
	v_fmac_f32_e32 v180, v126, v126
	v_fmac_f32_e32 v181, v128, v128
	v_cvt_pk_bf16_f32 v126, v126, v127
	v_cvt_pk_bf16_f32 v127, v128, v129
	v_lshl_add_u64 v[128:129], s[48:49], 0, v[140:141]
	v_lshl_add_u64 v[128:129], v[128:129], 0, v[178:179]
	global_store_dwordx2 v[128:129], v[126:127], off
	v_lshlrev_b32_e32 v126, 16, v192
	v_and_b32_e32 v127, 0xffff0000, v192
	v_pk_add_f32 v[122:123], v[122:123], v[126:127]
	v_lshlrev_b32_e32 v178, 16, v193
	v_and_b32_e32 v179, 0xffff0000, v193
	v_mul_f32_e32 v126, v123, v123
	v_pk_add_f32 v[124:125], v[124:125], v[178:179]
	v_fmac_f32_e32 v126, v122, v122
	v_cvt_pk_bf16_f32 v122, v122, v123
	v_cvt_pk_bf16_f32 v123, v124, v125
	v_mul_f32_e32 v127, v125, v125
	global_store_dwordx2 v[128:129], v[122:123], off offset:32
	v_lshlrev_b32_e32 v122, 16, v194
	v_and_b32_e32 v123, 0xffff0000, v194
	v_fmac_f32_e32 v127, v124, v124
	v_lshlrev_b32_e32 v124, 16, v195
	v_and_b32_e32 v125, 0xffff0000, v195
	v_pk_add_f32 v[118:119], v[118:119], v[122:123]
	v_pk_add_f32 v[120:121], v[120:121], v[124:125]
	v_mul_f32_e32 v122, v119, v119
	v_fmac_f32_e32 v122, v118, v118
	v_mul_f32_e32 v123, v121, v121
	v_cvt_pk_bf16_f32 v118, v118, v119
	v_cvt_pk_bf16_f32 v119, v120, v121
	v_fmac_f32_e32 v123, v120, v120
	global_store_dwordx2 v[128:129], v[118:119], off offset:256
	v_lshlrev_b32_e32 v118, 16, v196
	v_and_b32_e32 v119, 0xffff0000, v196
	v_lshlrev_b32_e32 v120, 16, v197
	v_and_b32_e32 v121, 0xffff0000, v197
	v_pk_add_f32 v[116:117], v[116:117], v[120:121]
	v_pk_add_f32 v[118:119], v[114:115], v[118:119]
	v_mul_f32_e32 v115, v117, v117
	v_mul_f32_e32 v114, v119, v119
	v_fmac_f32_e32 v114, v118, v118
	v_fmac_f32_e32 v115, v116, v116
	v_cvt_pk_bf16_f32 v118, v118, v119
	v_cvt_pk_bf16_f32 v119, v116, v117
	v_and_b32_e32 v116, 64, v216
	v_add_f32_e32 v180, v180, v181
	v_add_f32_e32 v126, v126, v127
	v_add_f32_e32 v114, v114, v115
	v_xor_b32_e32 v115, 16, v216
	v_add_u32_e32 v117, 64, v116
	v_add_f32_e32 v126, v180, v126
	v_add_f32_e32 v122, v122, v123
	v_cmp_lt_i32_e32 vcc, v115, v117
	v_add_f32_e32 v122, v126, v122
	v_add_f32_e32 v114, v122, v114
	v_cndmask_b32_e32 v115, v216, v115, vcc
	v_lshlrev_b32_e32 v116, 2, v115
	ds_bpermute_b32 v115, v116, v114
	global_store_dwordx2 v[128:129], v[118:119], off offset:288
	s_waitcnt lgkmcnt(0)
	v_add_f32_e32 v118, v114, v115
	v_xor_b32_e32 v114, 32, v216
	v_cmp_lt_i32_e32 vcc, v114, v117
	s_nop 1
	v_cndmask_b32_e32 v114, v216, v114, vcc
	v_lshlrev_b32_e32 v117, 2, v114
	ds_bpermute_b32 v119, v117, v118
	v_lshl_add_u64 v[114:115], v[170:171], 2, s[50:51]
	s_and_saveexec_b64 s[0:1], s[42:43]
	s_cbranch_execz .LBB0_95
	s_waitcnt lgkmcnt(0)
	v_add_f32_e32 v118, v118, v119
	global_atomic_add_f32 v[114:115], v118, off

; #define PG8_WAIT_V(n) asm volatile("s_waitcnt vmcnt(" #n ")" ::: "memory")
; #define PG8_BAR __builtin_amdgcn_s_barrier()
; template <class Epi, class Sched, bool ALIGN_EPI = false, bool SP2 = false>
; __device__ __forceinline__ void gemm_phase(PG8_LAS unsigned char* lds, const Gemm g, const Sched& S, const Epi& E, const int tid) {
;     ...
;     PG8_WAIT_V(0);
;     if constexpr (!ALIGN_EPI) { if (wr == 0) PG8_BAR; }
;     PG8_BAR;
.LBB0_109:
	s_waitcnt vmcnt(0)
	v_readlane_b32 s72, v254, 15
	s_cmpk_gt_u32 s13, 0xff
	v_readlane_b32 s71, v254, 14
	v_readlane_b32 s73, v254, 16
	s_mov_b32 s39, s59
	s_mov_b32 s62, s64
	s_cbranch_scc1 .LBB0_111
.LBB0_111:
	v_readlane_b32 s59, v254, 54
	s_barrier
